# v12 + lazy/closing residual epilogues (kinds 4, 5) also drain at each row-group
# speedup vs baseline: 1.0045x; 1.0045x over previous
;     static __device__ __forceinline__ void run(const f32x4 (&acc)[2][2][4][2], const Unit& u, int wr, int wc, int fr, int fq, const float* xin, float* xout, const float* gate, float gs, const float* lazy_ssq, const float* lazy_g, ...
;     ...
;             for (int m = 0; m < 4; ++m) { rl[ai][m] = LAZY ? __builtin_amdgcn_rsqf(lazy_ssq[row0 + ai * HALF + m * 16] * (1.0f / 1024.0f) + 1e-6f) : 1.0f; sq[ai][m] = 0.f; sqb[ai][m] = 0.f; }
; #pragma unroll
;         for (int bj = 0; bj < 2; ++bj) {
;             const unsigned col = col0 + bj * HALF;
;             f32x4 gv[2], lg[2], wv[2], w2[2];
; #pragma unroll
;             for (int n = 0; n < 2; ++n) {
;                 gv[n] = *(const f32x4*)(gate + (b * 9216u + col + 4 * n)) * gs;
;                 lg[n] = (f32x4){1.f, 1.f, 1.f, 1.f}; if (LAZY) lg[n] = *(const f32x4*)(lazy_g + col + 4 * n);
;                 wv[n] = (f32x4){0.f, 0.f, 0.f, 0.f}; w2[n] = (f32x4){1.f, 1.f, 1.f, 1.f};
;                 if (aout) { wv[n] = *(const f32x4*)(wg + col + 4 * n) * (*(const f32x4*)(wsc + (b * 9216u + col + 4 * n)) + 1.0f); if (WG2) { w2[n] = *(const f32x4*)(wg2 + col + 4 * n); wv[n] = wv[n] * w2[n]; } }
;             }
;             f32x4 xq[2][2][2];
;     ...
;             constexpr bool DEEP = !LAZY && !WG2;
;             if (DEEP) RES_LD(0, 0);
; #pragma unroll
;             for (int pp = 0; pp < 4; ++pp) {
;                 if (DEEP) { if (pp < 3) RES_LD((pp + 1) & 1, pp + 1); } else RES_LD(pp & 1, pp);
; #pragma unroll
;                 for (int j = 0; j < 2; ++j) { const int i_ = 2 * pp + j, ai = i_ >> 2, m = i_ & 3; const unsigned off = (row0 + ai * HALF + m * 16) * 1024u + col;
;                     const f32x4 xi0 = xq[pp & 1][j][0], xi1 = xq[pp & 1][j][1];
;                     f32x4 xo0 = gv[0] * acc[ai][bj][m][0], xo1 = gv[1] * acc[ai][bj][m][1];
;                     if (LAZY) { xo0 = xo0 + xi0 * lg[0] * rl[ai][m]; xo1 = xo1 + xi1 * lg[1] * rl[ai][m]; } else { xo0 = xo0 + xi0; xo1 = xo1 + xi1; }
;                     *(f32x4*)(xout + off) = xo0; *(f32x4*)(xout + off + 4) = xo1;
;                     if (aout) { const f32x4 a0 = xo0 * wv[0], a1 = xo1 * wv[1]; u32x4 w; w.x = cvt_pk_bf16(a0[0], a0[1]); w.y = cvt_pk_bf16(a0[2], a0[3]); w.z = cvt_pk_bf16(a1[0], a1[1]); w.w = cvt_pk_bf16(a1[2], a1[3]);
;                         *(u32x4*)(aout + off) = w;
.LBB0_319:
	v_lshlrev_b32_e32 v175, 10, v172
	v_add_u32_e32 v176, v184, v175
	v_lshlrev_b64 v[208:209], 2, v[176:177]
	s_waitcnt vmcnt(0)
	v_pk_mul_f32 v[204:205], s[36:37], v[136:137] op_sel_hi:[0,1]
	v_lshl_add_u64 v[136:137], s[34:35], 0, v[208:209]
	v_pk_mul_f32 v[200:201], s[36:37], v[140:141] op_sel_hi:[0,1]
	v_fmamk_f32 v140, v146, 0x3a800000, v222
	global_load_dwordx4 v[148:151], v[136:137], off offset:16
	global_load_dwordx4 v[144:147], v[136:137], off
	v_add_u32_e32 v190, 0x4000, v176
	v_mov_b32_e32 v191, v177
	v_rsq_f32_e32 v174, v140
	v_lshl_add_u64 v[140:141], v[190:191], 2, s[34:35]
	v_pk_mul_f32 v[198:199], s[36:37], v[142:143] op_sel_hi:[0,1]
	v_pk_mul_f32 v[202:203], s[36:37], v[138:139] op_sel_hi:[0,1]
	global_load_dwordx4 v[136:139], v[140:141], off offset:16
	s_nop 0
	global_load_dwordx4 v[140:143], v[140:141], off
	v_lshl_add_u64 v[208:209], s[30:31], 0, v[208:209]
	v_mov_b32_e32 v231, 0
	s_and_b64 vcc, exec, s[8:9]
	v_mov_b32_e32 v232, 0
	s_waitcnt vmcnt(0)
	v_pk_mul_f32 v[150:151], v[134:135], v[150:151]
	s_waitcnt vmcnt(0)
	v_pk_mul_f32 v[146:147], v[130:131], v[146:147]
	v_pk_mul_f32 v[144:145], v[128:129], v[144:145]
	v_pk_mul_f32 v[148:149], v[132:133], v[148:149]
	v_pk_mul_f32 v[146:147], v[174:175], v[146:147] op_sel_hi:[0,1]
	v_pk_mul_f32 v[144:145], v[174:175], v[144:145] op_sel_hi:[0,1]
	v_pk_mul_f32 v[150:151], v[174:175], v[150:151] op_sel_hi:[0,1]
	v_pk_mul_f32 v[148:149], v[174:175], v[148:149] op_sel_hi:[0,1]
	v_pk_fma_f32 v[144:145], v[124:125], v[204:205], v[144:145]
	v_pk_fma_f32 v[146:147], v[126:127], v[202:203], v[146:147]
	v_pk_fma_f32 v[148:149], v[120:121], v[200:201], v[148:149]
	v_pk_fma_f32 v[150:151], v[122:123], v[198:199], v[150:151]
	global_store_dwordx4 v[208:209], v[144:147], off
	global_store_dwordx4 v[208:209], v[148:151], off offset:16
	s_cbranch_vccnz .LBB0_321
	v_pk_mul_f32 v[208:209], v[188:189], v[146:147]
	v_pk_mul_f32 v[214:215], v[186:187], v[144:145]
	v_pk_mul_f32 v[234:235], v[192:193], v[148:149]
	v_cvt_pk_bf16_f32 v232, v214, v215
	v_cvt_pk_bf16_f32 v233, v208, v209
	v_lshl_add_u64 v[208:209], v[176:177], 1, s[28:29]
	v_pk_mul_f32 v[236:237], v[194:195], v[150:151]
	v_cvt_pk_bf16_f32 v234, v234, v235
	s_nop 0
	v_cvt_pk_bf16_f32 v235, v236, v237
	global_store_dwordx4 v[208:209], v[232:235], off
	v_mov_b32_e32 v209, v148
	v_mov_b32_e32 v148, v145
	v_mov_b32_e32 v208, v144
	v_pk_mul_f32 v[144:145], v[148:149], v[148:149]
	v_mov_b32_e32 v149, v150
	v_mov_b32_e32 v150, v147
	v_mov_b32_e32 v148, v146
	v_pk_mul_f32 v[146:147], v[150:151], v[150:151]
	v_pk_fma_f32 v[144:145], v[208:209], v[208:209], v[144:145]
	v_pk_fma_f32 v[146:147], v[148:149], v[148:149], v[146:147]
	s_nop 0
	v_pk_add_f32 v[144:145], v[144:145], v[146:147]
	s_nop 0
	v_add_f32_e32 v232, v144, v145
.LBB0_321:
	v_fmamk_f32 v144, v196, 0x3a800000, v222
	v_rsq_f32_e32 v196, v144
	s_waitcnt vmcnt(0)
	v_pk_mul_f32 v[142:143], v[130:131], v[142:143]
	v_pk_mul_f32 v[140:141], v[128:129], v[140:141]
	v_pk_mul_f32 v[138:139], v[134:135], v[138:139]
	v_pk_mul_f32 v[136:137], v[132:133], v[136:137]
	v_pk_mul_f32 v[142:143], v[196:197], v[142:143] op_sel_hi:[0,1]
	v_pk_mul_f32 v[140:141], v[196:197], v[140:141] op_sel_hi:[0,1]
	v_pk_mul_f32 v[138:139], v[196:197], v[138:139] op_sel_hi:[0,1]
	v_pk_mul_f32 v[136:137], v[196:197], v[136:137] op_sel_hi:[0,1]
	v_pk_fma_f32 v[142:143], v[110:111], v[202:203], v[142:143]
	v_pk_fma_f32 v[140:141], v[108:109], v[204:205], v[140:141]
	v_pk_fma_f32 v[138:139], v[106:107], v[198:199], v[138:139]
	v_pk_fma_f32 v[136:137], v[104:105], v[200:201], v[136:137]
	v_lshl_add_u64 v[144:145], v[190:191], 2, s[30:31]
	s_and_b64 vcc, exec, s[8:9]
	global_store_dwordx4 v[144:145], v[140:143], off
	global_store_dwordx4 v[144:145], v[136:139], off offset:16
	s_cbranch_vccnz .LBB0_323
	v_pk_mul_f32 v[146:147], v[188:189], v[142:143]
	v_pk_mul_f32 v[144:145], v[186:187], v[140:141]
	v_pk_mul_f32 v[148:149], v[194:195], v[138:139]
	v_pk_mul_f32 v[150:151], v[192:193], v[136:137]
	v_cvt_pk_bf16_f32 v144, v144, v145
	v_cvt_pk_bf16_f32 v145, v146, v147
	s_nop 0
	v_cvt_pk_bf16_f32 v146, v150, v151
	v_cvt_pk_bf16_f32 v147, v148, v149
	v_lshl_add_u64 v[148:149], v[190:191], 1, s[28:29]
	global_store_dwordx4 v[148:149], v[144:147], off
	s_nop 1
	v_mov_b32_e32 v145, v136
	v_mov_b32_e32 v136, v141
	v_mov_b32_e32 v141, v138
	v_mov_b32_e32 v138, v143
	v_mov_b32_e32 v144, v140
	v_pk_mul_f32 v[136:137], v[136:137], v[136:137]
	v_mov_b32_e32 v140, v142
	v_pk_mul_f32 v[138:139], v[138:139], v[138:139]
	v_pk_fma_f32 v[136:137], v[144:145], v[144:145], v[136:137]
	v_pk_fma_f32 v[138:139], v[140:141], v[140:141], v[138:139]
	s_nop 0
	v_pk_add_f32 v[136:137], v[136:137], v[138:139]
	s_nop 0
	v_add_f32_e32 v231, v136, v137
;     static __device__ __forceinline__ void run(const f32x4 (&acc)[2][2][4][2], const Unit& u, int wr, int wc, int fr, int fq, const float* xin, float* xout, const float* gate, float gs, const float* lazy_ssq, const float* lazy_g, ...
;     ...
;             for (int m = 0; m < 4; ++m) { rl[ai][m] = LAZY ? __builtin_amdgcn_rsqf(lazy_ssq[row0 + ai * HALF + m * 16] * (1.0f / 1024.0f) + 1e-6f) : 1.0f; sq[ai][m] = 0.f; sqb[ai][m] = 0.f; }
; #pragma unroll
;         for (int bj = 0; bj < 2; ++bj) {
;             const unsigned col = col0 + bj * HALF;
;             f32x4 gv[2], lg[2], wv[2], w2[2];
; #pragma unroll
;             for (int n = 0; n < 2; ++n) {
;                 gv[n] = *(const f32x4*)(gate + (b * 9216u + col + 4 * n)) * gs;
;                 lg[n] = (f32x4){1.f, 1.f, 1.f, 1.f}; if (LAZY) lg[n] = *(const f32x4*)(lazy_g + col + 4 * n);
;                 wv[n] = (f32x4){0.f, 0.f, 0.f, 0.f}; w2[n] = (f32x4){1.f, 1.f, 1.f, 1.f};
;                 if (aout) { wv[n] = *(const f32x4*)(wg + col + 4 * n) * (*(const f32x4*)(wsc + (b * 9216u + col + 4 * n)) + 1.0f); if (WG2) { w2[n] = *(const f32x4*)(wg2 + col + 4 * n); wv[n] = wv[n] * w2[n]; } }
;             }
;             f32x4 xq[2][2][2];
;     ...
;             constexpr bool DEEP = !LAZY && !WG2;
;             if (DEEP) RES_LD(0, 0);
; #pragma unroll
;             for (int pp = 0; pp < 4; ++pp) {
;                 if (DEEP) { if (pp < 3) RES_LD((pp + 1) & 1, pp + 1); } else RES_LD(pp & 1, pp);
; #pragma unroll
;                 for (int j = 0; j < 2; ++j) { const int i_ = 2 * pp + j, ai = i_ >> 2, m = i_ & 3; const unsigned off = (row0 + ai * HALF + m * 16) * 1024u + col;
;                     const f32x4 xi0 = xq[pp & 1][j][0], xi1 = xq[pp & 1][j][1];
;                     f32x4 xo0 = gv[0] * acc[ai][bj][m][0], xo1 = gv[1] * acc[ai][bj][m][1];
;                     if (LAZY) { xo0 = xo0 + xi0 * lg[0] * rl[ai][m]; xo1 = xo1 + xi1 * lg[1] * rl[ai][m]; } else { xo0 = xo0 + xi0; xo1 = xo1 + xi1; }
;                     *(f32x4*)(xout + off) = xo0; *(f32x4*)(xout + off + 4) = xo1;
;                     if (aout) { const f32x4 a0 = xo0 * wv[0], a1 = xo1 * wv[1]; u32x4 w; w.x = cvt_pk_bf16(a0[0], a0[1]); w.y = cvt_pk_bf16(a0[2], a0[3]); w.z = cvt_pk_bf16(a1[0], a1[1]); w.w = cvt_pk_bf16(a1[2], a1[3]);
;                         *(u32x4*)(aout + off) = w;
.LBB0_323:
	v_add_u32_e32 v208, 0x8000, v176
	v_mov_b32_e32 v209, v177
	v_fmamk_f32 v136, v206, 0x3a800000, v222
	v_lshlrev_b64 v[214:215], 2, v[208:209]
	v_rsq_f32_e32 v190, v136
	v_lshl_add_u64 v[136:137], s[34:35], 0, v[214:215]
	global_load_dwordx4 v[148:151], v[136:137], off offset:16
	global_load_dwordx4 v[144:147], v[136:137], off
	v_add_u32_e32 v206, 0xc000, v176
	v_mov_b32_e32 v207, v177
	v_lshl_add_u64 v[140:141], v[206:207], 2, s[34:35]
	global_load_dwordx4 v[136:139], v[140:141], off offset:16
	s_nop 0
	global_load_dwordx4 v[140:143], v[140:141], off
	v_lshl_add_u64 v[214:215], s[30:31], 0, v[214:215]
	v_mov_b32_e32 v233, 0
	s_and_b64 vcc, exec, s[8:9]
	v_mov_b32_e32 v234, 0
	s_waitcnt vmcnt(0)
	v_pk_mul_f32 v[150:151], v[134:135], v[150:151]
	s_waitcnt vmcnt(0)
	v_pk_mul_f32 v[146:147], v[130:131], v[146:147]
	v_pk_mul_f32 v[144:145], v[128:129], v[144:145]
	v_pk_mul_f32 v[148:149], v[132:133], v[148:149]
	v_pk_mul_f32 v[146:147], v[190:191], v[146:147] op_sel_hi:[0,1]
	v_pk_mul_f32 v[144:145], v[190:191], v[144:145] op_sel_hi:[0,1]
	v_pk_mul_f32 v[150:151], v[190:191], v[150:151] op_sel_hi:[0,1]
	v_pk_mul_f32 v[148:149], v[190:191], v[148:149] op_sel_hi:[0,1]
	v_pk_fma_f32 v[146:147], v[94:95], v[202:203], v[146:147]
	v_pk_fma_f32 v[144:145], v[92:93], v[204:205], v[144:145]
	v_pk_fma_f32 v[150:151], v[90:91], v[198:199], v[150:151]
	v_pk_fma_f32 v[148:149], v[88:89], v[200:201], v[148:149]
	global_store_dwordx4 v[214:215], v[144:147], off
	global_store_dwordx4 v[214:215], v[148:151], off offset:16
	s_cbranch_vccnz .LBB0_325
	v_pk_mul_f32 v[234:235], v[186:187], v[144:145]
	v_pk_mul_f32 v[236:237], v[192:193], v[148:149]
	v_lshl_add_u64 v[208:209], v[208:209], 1, s[28:29]
	v_pk_mul_f32 v[214:215], v[188:189], v[146:147]
	v_pk_mul_f32 v[238:239], v[194:195], v[150:151]
	v_cvt_pk_bf16_f32 v234, v234, v235
	v_cvt_pk_bf16_f32 v235, v214, v215
	v_cvt_pk_bf16_f32 v236, v236, v237
	s_nop 0
	v_cvt_pk_bf16_f32 v237, v238, v239
	global_store_dwordx4 v[208:209], v[234:237], off
	v_mov_b32_e32 v209, v148
	v_mov_b32_e32 v148, v145
	v_mov_b32_e32 v208, v144
	v_pk_mul_f32 v[144:145], v[148:149], v[148:149]
	v_mov_b32_e32 v149, v150
	v_mov_b32_e32 v150, v147
	v_mov_b32_e32 v148, v146
	v_pk_mul_f32 v[146:147], v[150:151], v[150:151]
	v_pk_fma_f32 v[144:145], v[208:209], v[208:209], v[144:145]
	v_pk_fma_f32 v[146:147], v[148:149], v[148:149], v[146:147]
	s_nop 0
	v_pk_add_f32 v[144:145], v[144:145], v[146:147]
	s_nop 0
	v_add_f32_e32 v234, v144, v145
.LBB0_325:
	v_fmamk_f32 v144, v210, 0x3a800000, v222
	v_rsq_f32_e32 v210, v144
	s_waitcnt vmcnt(0)
	v_pk_mul_f32 v[142:143], v[130:131], v[142:143]
	v_pk_mul_f32 v[140:141], v[128:129], v[140:141]
	v_pk_mul_f32 v[138:139], v[134:135], v[138:139]
	v_pk_mul_f32 v[136:137], v[132:133], v[136:137]
	v_pk_mul_f32 v[142:143], v[210:211], v[142:143] op_sel_hi:[0,1]
	v_pk_mul_f32 v[140:141], v[210:211], v[140:141] op_sel_hi:[0,1]
	v_pk_mul_f32 v[138:139], v[210:211], v[138:139] op_sel_hi:[0,1]
	v_pk_mul_f32 v[136:137], v[210:211], v[136:137] op_sel_hi:[0,1]
	v_pk_fma_f32 v[142:143], v[78:79], v[202:203], v[142:143]
	v_pk_fma_f32 v[140:141], v[76:77], v[204:205], v[140:141]
	v_pk_fma_f32 v[138:139], v[74:75], v[198:199], v[138:139]
	v_pk_fma_f32 v[136:137], v[72:73], v[200:201], v[136:137]
	v_lshl_add_u64 v[144:145], v[206:207], 2, s[30:31]
	s_and_b64 vcc, exec, s[8:9]
	global_store_dwordx4 v[144:145], v[140:143], off
	global_store_dwordx4 v[144:145], v[136:139], off offset:16
	s_cbranch_vccnz .LBB0_327
	v_pk_mul_f32 v[146:147], v[188:189], v[142:143]
	v_pk_mul_f32 v[144:145], v[186:187], v[140:141]
	v_pk_mul_f32 v[148:149], v[194:195], v[138:139]
	v_pk_mul_f32 v[150:151], v[192:193], v[136:137]
	v_cvt_pk_bf16_f32 v144, v144, v145
	v_cvt_pk_bf16_f32 v145, v146, v147
	s_nop 0
	v_cvt_pk_bf16_f32 v146, v150, v151
	v_cvt_pk_bf16_f32 v147, v148, v149
	v_lshl_add_u64 v[148:149], v[206:207], 1, s[28:29]
	global_store_dwordx4 v[148:149], v[144:147], off
	s_nop 1
	v_mov_b32_e32 v145, v136
	v_mov_b32_e32 v136, v141
	v_mov_b32_e32 v141, v138
	v_mov_b32_e32 v138, v143
	v_mov_b32_e32 v144, v140
	v_pk_mul_f32 v[136:137], v[136:137], v[136:137]
	v_mov_b32_e32 v140, v142
	v_pk_mul_f32 v[138:139], v[138:139], v[138:139]
	v_pk_fma_f32 v[136:137], v[144:145], v[144:145], v[136:137]
	v_pk_fma_f32 v[138:139], v[140:141], v[140:141], v[138:139]
	s_nop 0
	v_pk_add_f32 v[136:137], v[136:137], v[138:139]
	s_nop 0
	v_add_f32_e32 v233, v136, v137
;     static __device__ __forceinline__ void run(const f32x4 (&acc)[2][2][4][2], const Unit& u, int wr, int wc, int fr, int fq, const float* xin, float* xout, const float* gate, float gs, const float* lazy_ssq, const float* lazy_g, ...
;     ...
;             for (int m = 0; m < 4; ++m) { rl[ai][m] = LAZY ? __builtin_amdgcn_rsqf(lazy_ssq[row0 + ai * HALF + m * 16] * (1.0f / 1024.0f) + 1e-6f) : 1.0f; sq[ai][m] = 0.f; sqb[ai][m] = 0.f; }
; #pragma unroll
;         for (int bj = 0; bj < 2; ++bj) {
;             const unsigned col = col0 + bj * HALF;
;             f32x4 gv[2], lg[2], wv[2], w2[2];
; #pragma unroll
;             for (int n = 0; n < 2; ++n) {
;                 gv[n] = *(const f32x4*)(gate + (b * 9216u + col + 4 * n)) * gs;
;                 lg[n] = (f32x4){1.f, 1.f, 1.f, 1.f}; if (LAZY) lg[n] = *(const f32x4*)(lazy_g + col + 4 * n);
;                 wv[n] = (f32x4){0.f, 0.f, 0.f, 0.f}; w2[n] = (f32x4){1.f, 1.f, 1.f, 1.f};
;                 if (aout) { wv[n] = *(const f32x4*)(wg + col + 4 * n) * (*(const f32x4*)(wsc + (b * 9216u + col + 4 * n)) + 1.0f); if (WG2) { w2[n] = *(const f32x4*)(wg2 + col + 4 * n); wv[n] = wv[n] * w2[n]; } }
;             }
;             f32x4 xq[2][2][2];
;     ...
;             constexpr bool DEEP = !LAZY && !WG2;
;             if (DEEP) RES_LD(0, 0);
; #pragma unroll
;             for (int pp = 0; pp < 4; ++pp) {
;                 if (DEEP) { if (pp < 3) RES_LD((pp + 1) & 1, pp + 1); } else RES_LD(pp & 1, pp);
; #pragma unroll
;                 for (int j = 0; j < 2; ++j) { const int i_ = 2 * pp + j, ai = i_ >> 2, m = i_ & 3; const unsigned off = (row0 + ai * HALF + m * 16) * 1024u + col;
;                     const f32x4 xi0 = xq[pp & 1][j][0], xi1 = xq[pp & 1][j][1];
;                     f32x4 xo0 = gv[0] * acc[ai][bj][m][0], xo1 = gv[1] * acc[ai][bj][m][1];
;                     if (LAZY) { xo0 = xo0 + xi0 * lg[0] * rl[ai][m]; xo1 = xo1 + xi1 * lg[1] * rl[ai][m]; } else { xo0 = xo0 + xi0; xo1 = xo1 + xi1; }
;                     *(f32x4*)(xout + off) = xo0; *(f32x4*)(xout + off + 4) = xo1;
;                     if (aout) { const f32x4 a0 = xo0 * wv[0], a1 = xo1 * wv[1]; u32x4 w; w.x = cvt_pk_bf16(a0[0], a0[1]); w.y = cvt_pk_bf16(a0[2], a0[3]); w.z = cvt_pk_bf16(a1[0], a1[1]); w.w = cvt_pk_bf16(a1[2], a1[3]);
;                         *(u32x4*)(aout + off) = w;
.LBB0_327:
	s_nop 0
	v_fmamk_f32 v136, v213, 0x3a800000, v222
	v_lshlrev_b32_e32 v213, 10, v158
	v_add_u32_e32 v214, v213, v184
	v_mov_b32_e32 v215, v177
	v_rsq_f32_e32 v206, v136
	v_lshl_add_u64 v[136:137], v[214:215], 2, s[34:35]
	global_load_dwordx4 v[148:151], v[136:137], off offset:16
	global_load_dwordx4 v[144:147], v[136:137], off
	v_add_u32_e32 v136, 0x4000, v214
	v_mov_b32_e32 v137, v177
	v_lshl_add_u64 v[140:141], v[136:137], 2, s[34:35]
	global_load_dwordx4 v[136:139], v[140:141], off offset:16
	s_nop 0
	global_load_dwordx4 v[140:143], v[140:141], off
	v_add_u32_e32 v208, 0x20000, v176
	v_mov_b32_e32 v209, v177
	v_lshl_add_u64 v[236:237], v[208:209], 2, s[30:31]
	v_mov_b32_e32 v235, 0
	s_and_b64 vcc, exec, s[8:9]
	s_waitcnt vmcnt(0)
	v_pk_mul_f32 v[150:151], v[134:135], v[150:151]
	s_waitcnt vmcnt(0)
	v_pk_mul_f32 v[146:147], v[130:131], v[146:147]
	v_pk_mul_f32 v[144:145], v[128:129], v[144:145]
	v_pk_mul_f32 v[146:147], v[206:207], v[146:147] op_sel_hi:[0,1]
	v_pk_mul_f32 v[144:145], v[206:207], v[144:145] op_sel_hi:[0,1]
	v_pk_mul_f32 v[148:149], v[132:133], v[148:149]
	v_pk_fma_f32 v[146:147], v[62:63], v[202:203], v[146:147]
	v_pk_fma_f32 v[144:145], v[60:61], v[204:205], v[144:145]
	v_pk_mul_f32 v[150:151], v[206:207], v[150:151] op_sel_hi:[0,1]
	v_pk_mul_f32 v[148:149], v[206:207], v[148:149] op_sel_hi:[0,1]
	v_pk_fma_f32 v[150:151], v[58:59], v[198:199], v[150:151]
	v_pk_fma_f32 v[148:149], v[56:57], v[200:201], v[148:149]
	global_store_dwordx4 v[236:237], v[144:147], off
	global_store_dwordx4 v[236:237], v[148:151], off offset:16
	v_mov_b32_e32 v236, 0
	s_cbranch_vccnz .LBB0_329
	v_pk_mul_f32 v[238:239], v[188:189], v[146:147]
	v_pk_mul_f32 v[236:237], v[186:187], v[144:145]
	v_lshl_add_u64 v[208:209], v[208:209], 1, s[28:29]
	v_pk_mul_f32 v[240:241], v[194:195], v[150:151]
	v_pk_mul_f32 v[242:243], v[192:193], v[148:149]
	v_cvt_pk_bf16_f32 v236, v236, v237
	v_cvt_pk_bf16_f32 v237, v238, v239
	s_nop 0
	v_cvt_pk_bf16_f32 v238, v242, v243
	v_cvt_pk_bf16_f32 v239, v240, v241
	global_store_dwordx4 v[208:209], v[236:239], off
	v_mov_b32_e32 v209, v148
	v_mov_b32_e32 v148, v145
	v_mov_b32_e32 v208, v144
	v_pk_mul_f32 v[144:145], v[148:149], v[148:149]
	v_mov_b32_e32 v149, v150
	v_mov_b32_e32 v150, v147
	v_mov_b32_e32 v148, v146
	v_pk_mul_f32 v[146:147], v[150:151], v[150:151]
	v_pk_fma_f32 v[144:145], v[208:209], v[208:209], v[144:145]
	v_pk_fma_f32 v[146:147], v[148:149], v[148:149], v[146:147]
	s_nop 0
	v_pk_add_f32 v[144:145], v[144:145], v[146:147]
	s_nop 0
	v_add_f32_e32 v236, v144, v145
.LBB0_329:
	v_fmamk_f32 v144, v212, 0x3a800000, v222
	v_rsq_f32_e32 v212, v144
	s_waitcnt vmcnt(0)
	v_pk_mul_f32 v[142:143], v[130:131], v[142:143]
	v_pk_mul_f32 v[140:141], v[128:129], v[140:141]
	v_pk_mul_f32 v[138:139], v[134:135], v[138:139]
	v_pk_mul_f32 v[136:137], v[132:133], v[136:137]
	v_add_u32_e32 v144, 0x24000, v176
	v_pk_mul_f32 v[142:143], v[212:213], v[142:143] op_sel_hi:[0,1]
	v_pk_mul_f32 v[140:141], v[212:213], v[140:141] op_sel_hi:[0,1]
	v_pk_mul_f32 v[138:139], v[212:213], v[138:139] op_sel_hi:[0,1]
	v_pk_mul_f32 v[136:137], v[212:213], v[136:137] op_sel_hi:[0,1]
	v_mov_b32_e32 v145, v177
	v_pk_fma_f32 v[142:143], v[46:47], v[202:203], v[142:143]
	v_pk_fma_f32 v[140:141], v[44:45], v[204:205], v[140:141]
	v_pk_fma_f32 v[138:139], v[42:43], v[198:199], v[138:139]
	v_pk_fma_f32 v[136:137], v[40:41], v[200:201], v[136:137]
	v_lshl_add_u64 v[146:147], v[144:145], 2, s[30:31]
	s_and_b64 vcc, exec, s[8:9]
	global_store_dwordx4 v[146:147], v[140:143], off
	global_store_dwordx4 v[146:147], v[136:139], off offset:16
	s_cbranch_vccnz .LBB0_331
	v_pk_mul_f32 v[148:149], v[188:189], v[142:143]
	v_pk_mul_f32 v[146:147], v[186:187], v[140:141]
	v_lshl_add_u64 v[144:145], v[144:145], 1, s[28:29]
	v_pk_mul_f32 v[150:151], v[194:195], v[138:139]
	v_pk_mul_f32 v[208:209], v[192:193], v[136:137]
	v_cvt_pk_bf16_f32 v146, v146, v147
	v_cvt_pk_bf16_f32 v147, v148, v149
	s_nop 0
	v_cvt_pk_bf16_f32 v148, v208, v209
	v_cvt_pk_bf16_f32 v149, v150, v151
	global_store_dwordx4 v[144:145], v[146:149], off
	v_mov_b32_e32 v145, v136
	v_mov_b32_e32 v136, v141
	v_mov_b32_e32 v141, v138
	v_mov_b32_e32 v138, v143
	v_mov_b32_e32 v144, v140
	v_pk_mul_f32 v[136:137], v[136:137], v[136:137]
	v_mov_b32_e32 v140, v142
	v_pk_mul_f32 v[138:139], v[138:139], v[138:139]
	v_pk_fma_f32 v[136:137], v[144:145], v[144:145], v[136:137]
	v_pk_fma_f32 v[138:139], v[140:141], v[140:141], v[138:139]
	s_nop 0
	v_pk_add_f32 v[136:137], v[136:137], v[138:139]
	s_nop 0
	v_add_f32_e32 v235, v136, v137
; __device__ __forceinline__ unsigned cvt_pk_bf16(float lo, float hi) { unsigned r; asm volatile("v_cvt_pk_bf16_f32 %0, %1, %2" : "=v"(r) : "v"(lo), "v"(hi)); return r; }
; #define RES_LD(buf, pp) do { _Pragma("unroll") for (int j = 0; j < 2; ++j) { const int i_ = 2 * (pp) + j; const unsigned off_ = (row0 + (i_ >> 2) * HALF + (i_ & 3) * 16) * 1024u + col; \
;                 xq[buf][j][0] = *(const f32x4*)(xin + off_); xq[buf][j][1] = *(const f32x4*)(xin + off_ + 4); } } while (0)
;     static __device__ __forceinline__ void run(const f32x4 (&acc)[2][2][4][2], const Unit& u, int wr, int wc, int fr, int fq, const float* xin, float* xout, const float* gate, float gs, const float* lazy_ssq, const float* lazy_g, ...
;     ...
;             constexpr bool DEEP = !LAZY && !WG2;
;             if (DEEP) RES_LD(0, 0);
; #pragma unroll
;             for (int pp = 0; pp < 4; ++pp) {
;                 if (DEEP) { if (pp < 3) RES_LD((pp + 1) & 1, pp + 1); } else RES_LD(pp & 1, pp);
; #pragma unroll
;                 for (int j = 0; j < 2; ++j) { const int i_ = 2 * pp + j, ai = i_ >> 2, m = i_ & 3; const unsigned off = (row0 + ai * HALF + m * 16) * 1024u + col;
;                     const f32x4 xi0 = xq[pp & 1][j][0], xi1 = xq[pp & 1][j][1];
;                     f32x4 xo0 = gv[0] * acc[ai][bj][m][0], xo1 = gv[1] * acc[ai][bj][m][1];
;                     if (LAZY) { xo0 = xo0 + xi0 * lg[0] * rl[ai][m]; xo1 = xo1 + xi1 * lg[1] * rl[ai][m]; } else { xo0 = xo0 + xi0; xo1 = xo1 + xi1; }
;                     *(f32x4*)(xout + off) = xo0; *(f32x4*)(xout + off + 4) = xo1;
;                     if (aout) { const f32x4 a0 = xo0 * wv[0], a1 = xo1 * wv[1]; u32x4 w; w.x = cvt_pk_bf16(a0[0], a0[1]); w.y = cvt_pk_bf16(a0[2], a0[3]); w.z = cvt_pk_bf16(a1[0], a1[1]); w.w = cvt_pk_bf16(a1[2], a1[3]);
;                         *(u32x4*)(aout + off) = w;
;                         sq[ai][m] += ((xo0[0] * xo0[0] + xo0[1] * xo0[1]) + (xo0[2] * xo0[2] + xo0[3] * xo0[3])) + ((xo1[0] * xo1[0] + xo1[1] * xo1[1]) + (xo1[2] * xo1[2] + xo1[3] * xo1[3]));
;                         if (WG2) { const f32x4 b0 = xo0 * w2[0], b1 = xo1 * w2[1]; sqb[ai][m] += ((b0[0] * b0[0] + b0[1] * b0[1]) + (b0[2] * b0[2] + b0[3] * b0[3])) + ((b1[0] * b1[0] + b1[1] * b1[1]) + (b1[2] * b1[2] + b1[3] * b1[3])); } } }
.LBB0_331:
	s_nop 0
	v_fmamk_f32 v136, v211, 0x3a800000, v222
	v_rsq_f32_e32 v208, v136
	v_add_u32_e32 v136, 0x8000, v214
	v_mov_b32_e32 v137, v177
	v_lshl_add_u64 v[136:137], v[136:137], 2, s[34:35]
	global_load_dwordx4 v[148:151], v[136:137], off offset:16
	global_load_dwordx4 v[144:147], v[136:137], off
	v_add_u32_e32 v136, 0xc000, v214
	v_mov_b32_e32 v137, v177
	v_lshl_add_u64 v[140:141], v[136:137], 2, s[34:35]
	global_load_dwordx4 v[136:139], v[140:141], off offset:16
	s_nop 0
	global_load_dwordx4 v[140:143], v[140:141], off
	v_add_u32_e32 v214, 0x28000, v176
	v_mov_b32_e32 v215, v177
	v_lshl_add_u64 v[238:239], v[214:215], 2, s[30:31]
	v_mov_b32_e32 v237, 0
	s_and_b64 vcc, exec, s[8:9]
	s_waitcnt vmcnt(0)
	v_pk_mul_f32 v[150:151], v[134:135], v[150:151]
	s_waitcnt vmcnt(0)
	v_pk_mul_f32 v[146:147], v[130:131], v[146:147]
	v_pk_mul_f32 v[144:145], v[128:129], v[144:145]
	v_pk_mul_f32 v[146:147], v[208:209], v[146:147] op_sel_hi:[0,1]
	v_pk_mul_f32 v[144:145], v[208:209], v[144:145] op_sel_hi:[0,1]
	v_pk_mul_f32 v[148:149], v[132:133], v[148:149]
	v_pk_fma_f32 v[146:147], v[30:31], v[202:203], v[146:147]
	v_pk_fma_f32 v[144:145], v[28:29], v[204:205], v[144:145]
	v_pk_mul_f32 v[150:151], v[208:209], v[150:151] op_sel_hi:[0,1]
	v_pk_mul_f32 v[148:149], v[208:209], v[148:149] op_sel_hi:[0,1]
	v_pk_fma_f32 v[150:151], v[26:27], v[198:199], v[150:151]
	v_pk_fma_f32 v[148:149], v[24:25], v[200:201], v[148:149]
	global_store_dwordx4 v[238:239], v[144:147], off
	global_store_dwordx4 v[238:239], v[148:151], off offset:16
	v_mov_b32_e32 v238, 0
	s_cbranch_vccnz .LBB0_333
	v_pk_mul_f32 v[240:241], v[188:189], v[146:147]
	v_pk_mul_f32 v[238:239], v[186:187], v[144:145]
	v_lshl_add_u64 v[214:215], v[214:215], 1, s[28:29]
	v_pk_mul_f32 v[242:243], v[194:195], v[150:151]
	v_pk_mul_f32 v[244:245], v[192:193], v[148:149]
	v_cvt_pk_bf16_f32 v238, v238, v239
	v_cvt_pk_bf16_f32 v239, v240, v241
	s_nop 0
	v_cvt_pk_bf16_f32 v240, v244, v245
	v_cvt_pk_bf16_f32 v241, v242, v243
	global_store_dwordx4 v[214:215], v[238:241], off
	v_mov_b32_e32 v215, v148
	v_mov_b32_e32 v148, v145
	v_mov_b32_e32 v214, v144
	v_pk_mul_f32 v[144:145], v[148:149], v[148:149]
	v_mov_b32_e32 v149, v150
	v_mov_b32_e32 v150, v147
	v_mov_b32_e32 v148, v146
	v_pk_mul_f32 v[146:147], v[150:151], v[150:151]
	v_pk_fma_f32 v[144:145], v[214:215], v[214:215], v[144:145]
	v_pk_fma_f32 v[146:147], v[148:149], v[148:149], v[146:147]
	s_nop 0
	v_pk_add_f32 v[144:145], v[144:145], v[146:147]
	s_nop 0
	v_add_f32_e32 v238, v144, v145
.LBB0_333:
	v_fmamk_f32 v144, v197, 0x3a800000, v222
	v_rsq_f32_e32 v214, v144
	s_waitcnt vmcnt(0)
	v_pk_mul_f32 v[130:131], v[130:131], v[142:143]
	v_pk_mul_f32 v[128:129], v[128:129], v[140:141]
	v_pk_mul_f32 v[134:135], v[134:135], v[138:139]
	v_pk_mul_f32 v[132:133], v[132:133], v[136:137]
	v_add_u32_e32 v176, 0x2c000, v176
	v_pk_mul_f32 v[130:131], v[214:215], v[130:131] op_sel_hi:[0,1]
	v_pk_mul_f32 v[128:129], v[214:215], v[128:129] op_sel_hi:[0,1]
	v_pk_mul_f32 v[134:135], v[214:215], v[134:135] op_sel_hi:[0,1]
	v_pk_mul_f32 v[132:133], v[214:215], v[132:133] op_sel_hi:[0,1]
	v_pk_fma_f32 v[130:131], v[14:15], v[202:203], v[130:131]
	v_pk_fma_f32 v[128:129], v[12:13], v[204:205], v[128:129]
	v_pk_fma_f32 v[134:135], v[10:11], v[198:199], v[134:135]
	v_pk_fma_f32 v[132:133], v[8:9], v[200:201], v[132:133]
	v_lshl_add_u64 v[136:137], v[176:177], 2, s[30:31]
	s_and_b64 vcc, exec, s[8:9]
	global_store_dwordx4 v[136:137], v[128:131], off
	global_store_dwordx4 v[136:137], v[132:135], off offset:16
	s_cbranch_vccnz .LBB0_335
	v_pk_mul_f32 v[138:139], v[188:189], v[130:131]
	v_pk_mul_f32 v[136:137], v[186:187], v[128:129]
	v_pk_mul_f32 v[140:141], v[194:195], v[134:135]
	v_pk_mul_f32 v[142:143], v[192:193], v[132:133]
	v_cvt_pk_bf16_f32 v136, v136, v137
	v_cvt_pk_bf16_f32 v137, v138, v139
	s_nop 0
	v_cvt_pk_bf16_f32 v138, v142, v143
	v_cvt_pk_bf16_f32 v139, v140, v141
	v_lshl_add_u64 v[140:141], v[176:177], 1, s[28:29]
	global_store_dwordx4 v[140:141], v[136:139], off
	s_nop 1
	v_mov_b32_e32 v137, v132
	v_mov_b32_e32 v132, v129
	v_mov_b32_e32 v136, v128
	v_pk_mul_f32 v[128:129], v[132:133], v[132:133]
	v_mov_b32_e32 v133, v134
	v_mov_b32_e32 v134, v131
	v_mov_b32_e32 v132, v130
	v_pk_mul_f32 v[130:131], v[134:135], v[134:135]
	v_pk_fma_f32 v[128:129], v[136:137], v[136:137], v[128:129]
	v_pk_fma_f32 v[130:131], v[132:133], v[132:133], v[130:131]
	s_nop 0
	v_pk_add_f32 v[128:129], v[128:129], v[130:131]
	s_nop 0
	v_add_f32_e32 v237, v128, v129

;     static __device__ __forceinline__ void run(const f32x4 (&acc)[2][2][4][2], const Unit& u, int wr, int wc, int fr, int fq, const float* xin, float* xout, const float* gate, float gs, const float* lazy_ssq, const float* lazy_g, ...
;     ...
;                 gv[n] = *(const f32x4*)(gate + (b * 9216u + col + 4 * n)) * gs;
;                 lg[n] = (f32x4){1.f, 1.f, 1.f, 1.f}; if (LAZY) lg[n] = *(const f32x4*)(lazy_g + col + 4 * n);
;                 wv[n] = (f32x4){0.f, 0.f, 0.f, 0.f}; w2[n] = (f32x4){1.f, 1.f, 1.f, 1.f};
;                 if (aout) { wv[n] = *(const f32x4*)(wg + col + 4 * n) * (*(const f32x4*)(wsc + (b * 9216u + col + 4 * n)) + 1.0f); if (WG2) { w2[n] = *(const f32x4*)(wg2 + col + 4 * n); wv[n] = wv[n] * w2[n]; } }
;             }
;             f32x4 xq[2][2][2];
;     ...
;             constexpr bool DEEP = !LAZY && !WG2;
;             if (DEEP) RES_LD(0, 0);
; #pragma unroll
;             for (int pp = 0; pp < 4; ++pp) {
;                 if (DEEP) { if (pp < 3) RES_LD((pp + 1) & 1, pp + 1); } else RES_LD(pp & 1, pp);
; #pragma unroll
;                 for (int j = 0; j < 2; ++j) { const int i_ = 2 * pp + j, ai = i_ >> 2, m = i_ & 3; const unsigned off = (row0 + ai * HALF + m * 16) * 1024u + col;
;                     const f32x4 xi0 = xq[pp & 1][j][0], xi1 = xq[pp & 1][j][1];
;                     f32x4 xo0 = gv[0] * acc[ai][bj][m][0], xo1 = gv[1] * acc[ai][bj][m][1];
;                     if (LAZY) { xo0 = xo0 + xi0 * lg[0] * rl[ai][m]; xo1 = xo1 + xi1 * lg[1] * rl[ai][m]; } else { xo0 = xo0 + xi0; xo1 = xo1 + xi1; }
;                     *(f32x4*)(xout + off) = xo0; *(f32x4*)(xout + off + 4) = xo1;
;                     if (aout) { const f32x4 a0 = xo0 * wv[0], a1 = xo1 * wv[1]; u32x4 w; w.x = cvt_pk_bf16(a0[0], a0[1]); w.y = cvt_pk_bf16(a0[2], a0[3]); w.z = cvt_pk_bf16(a1[0], a1[1]); w.w = cvt_pk_bf16(a1[2], a1[3]);
;                         *(u32x4*)(aout + off) = w;
;                         sq[ai][m] += ((xo0[0] * xo0[0] + xo0[1] * xo0[1]) + (xo0[2] * xo0[2] + xo0[3] * xo0[3])) + ((xo1[0] * xo1[0] + xo1[1] * xo1[1]) + (xo1[2] * xo1[2] + xo1[3] * xo1[3]));
;                         if (WG2) { const f32x4 b0 = xo0 * w2[0], b1 = xo1 * w2[1]; sqb[ai][m] += ((b0[0] * b0[0] + b0[1] * b0[1]) + (b0[2] * b0[2] + b0[3] * b0[3])) + ((b1[0] * b1[0] + b1[1] * b1[1]) + (b1[2] * b1[2] + b1[3] * b1[3])); } } }
.LBB0_339:
	v_add_u32_e32 v176, v202, v175
	v_lshlrev_b64 v[204:205], 2, v[176:177]
	v_lshl_add_u64 v[136:137], s[34:35], 0, v[204:205]
	global_load_dwordx4 v[240:243], v[136:137], off
	global_load_dwordx4 v[244:247], v[136:137], off offset:16
	v_mov_b32_e32 v201, v177
	v_add_u32_e32 v200, 0x4000, v176
	v_lshl_add_u64 v[144:145], v[200:201], 2, s[34:35]
	global_load_dwordx4 v[136:139], v[144:145], off offset:16
	s_nop 0
	global_load_dwordx4 v[144:147], v[144:145], off
	s_mov_b32 s37, s36
	s_mov_b32 s38, s36
	s_mov_b32 s39, s36
	v_mov_b32_e32 v175, v174
	v_mov_b32_e32 v248, v174
	v_mov_b32_e32 v249, v174
	s_waitcnt vmcnt(0)
	v_pk_mul_f32 v[182:183], s[38:39], v[150:151]
	v_pk_mul_f32 v[192:193], s[36:37], v[148:149]
	v_pk_mul_f32 v[194:195], s[38:39], v[142:143]
	v_pk_mul_f32 v[198:199], s[36:37], v[140:141]
	s_and_b64 vcc, exec, s[8:9]
	v_lshl_add_u64 v[204:205], s[30:31], 0, v[204:205]
	s_waitcnt vmcnt(0)
	v_pk_mul_f32 v[140:141], v[130:131], v[242:243]
	v_pk_mul_f32 v[142:143], v[128:129], v[240:241]
	s_waitcnt vmcnt(0)
	v_pk_mul_f32 v[148:149], v[134:135], v[246:247]
	v_pk_mul_f32 v[150:151], v[132:133], v[244:245]
	v_pk_mul_f32 v[140:141], v[248:249], v[140:141]
	v_pk_mul_f32 v[142:143], v[174:175], v[142:143]
	v_pk_mul_f32 v[240:241], v[248:249], v[148:149]
	v_pk_mul_f32 v[174:175], v[174:175], v[150:151]
	v_pk_fma_f32 v[150:151], v[118:119], v[194:195], v[140:141]
	v_pk_fma_f32 v[148:149], v[116:117], v[198:199], v[142:143]
	v_pk_fma_f32 v[142:143], v[114:115], v[182:183], v[240:241]
	v_pk_fma_f32 v[140:141], v[112:113], v[192:193], v[174:175]
	global_store_dwordx4 v[204:205], v[148:151], off
	global_store_dwordx4 v[204:205], v[140:143], off offset:16
	s_cbranch_vccnz .LBB0_341
	v_pk_mul_f32 v[174:175], v[188:189], v[150:151]
	v_pk_mul_f32 v[204:205], v[186:187], v[148:149]
	v_pk_mul_f32 v[242:243], v[184:185], v[140:141]
	v_cvt_pk_bf16_f32 v240, v204, v205
	v_cvt_pk_bf16_f32 v241, v174, v175
	v_lshl_add_u64 v[174:175], v[176:177], 1, s[28:29]
	v_pk_mul_f32 v[244:245], v[180:181], v[142:143]
	v_cvt_pk_bf16_f32 v242, v242, v243
	s_nop 0
	v_cvt_pk_bf16_f32 v243, v244, v245
	global_store_dwordx4 v[174:175], v[240:243], off
	v_mov_b32_e32 v175, v140
	v_mov_b32_e32 v140, v149
	v_mov_b32_e32 v149, v142
	v_mov_b32_e32 v142, v151
	v_mov_b32_e32 v174, v148
	v_pk_mul_f32 v[140:141], v[140:141], v[140:141]
	v_mov_b32_e32 v148, v150
	v_pk_mul_f32 v[142:143], v[142:143], v[142:143]
	v_pk_fma_f32 v[140:141], v[174:175], v[174:175], v[140:141]
	v_pk_fma_f32 v[142:143], v[148:149], v[148:149], v[142:143]
	s_nop 0
	v_pk_add_f32 v[140:141], v[140:141], v[142:143]
	s_nop 0
	v_add_f32_e32 v140, v140, v141
	v_add_f32_e32 v232, v232, v140
.LBB0_341:
	v_mov_b32_e32 v197, v196
	s_waitcnt vmcnt(0)
	v_pk_mul_f32 v[140:141], v[130:131], v[146:147]
	v_pk_mul_f32 v[142:143], v[128:129], v[144:145]
	v_mov_b32_e32 v144, v196
	v_mov_b32_e32 v145, v196
	v_pk_mul_f32 v[138:139], v[134:135], v[138:139]
	v_pk_mul_f32 v[136:137], v[132:133], v[136:137]
	v_pk_mul_f32 v[140:141], v[144:145], v[140:141]
	v_pk_mul_f32 v[146:147], v[196:197], v[142:143]
	v_pk_mul_f32 v[138:139], v[144:145], v[138:139]
	v_pk_mul_f32 v[136:137], v[196:197], v[136:137]
	v_pk_fma_f32 v[142:143], v[102:103], v[194:195], v[140:141]
	v_pk_fma_f32 v[140:141], v[100:101], v[198:199], v[146:147]
	v_pk_fma_f32 v[138:139], v[98:99], v[182:183], v[138:139]
	v_pk_fma_f32 v[136:137], v[96:97], v[192:193], v[136:137]
	v_lshl_add_u64 v[144:145], v[200:201], 2, s[30:31]
	s_and_b64 vcc, exec, s[8:9]
	global_store_dwordx4 v[144:145], v[140:143], off
	global_store_dwordx4 v[144:145], v[136:139], off offset:16
	s_cbranch_vccnz .LBB0_343
	v_pk_mul_f32 v[146:147], v[188:189], v[142:143]
	v_pk_mul_f32 v[144:145], v[186:187], v[140:141]
	v_pk_mul_f32 v[148:149], v[180:181], v[138:139]
	v_pk_mul_f32 v[150:151], v[184:185], v[136:137]
	v_cvt_pk_bf16_f32 v144, v144, v145
	v_cvt_pk_bf16_f32 v145, v146, v147
	s_nop 0
	v_cvt_pk_bf16_f32 v146, v150, v151
	v_cvt_pk_bf16_f32 v147, v148, v149
	v_lshl_add_u64 v[148:149], v[200:201], 1, s[28:29]
	global_store_dwordx4 v[148:149], v[144:147], off
	s_nop 1
	v_mov_b32_e32 v145, v136
	v_mov_b32_e32 v136, v141
	v_mov_b32_e32 v141, v138
	v_mov_b32_e32 v138, v143
	v_mov_b32_e32 v144, v140
	v_pk_mul_f32 v[136:137], v[136:137], v[136:137]
	v_mov_b32_e32 v140, v142
	v_pk_mul_f32 v[138:139], v[138:139], v[138:139]
	v_pk_fma_f32 v[136:137], v[144:145], v[144:145], v[136:137]
	v_pk_fma_f32 v[138:139], v[140:141], v[140:141], v[138:139]
	s_nop 0
	v_pk_add_f32 v[136:137], v[136:137], v[138:139]
	s_nop 0
	v_add_f32_e32 v136, v136, v137
	v_add_f32_e32 v231, v231, v136
; __device__ __forceinline__ unsigned cvt_pk_bf16(float lo, float hi) { unsigned r; asm volatile("v_cvt_pk_bf16_f32 %0, %1, %2" : "=v"(r) : "v"(lo), "v"(hi)); return r; }
; #define RES_LD(buf, pp) do { _Pragma("unroll") for (int j = 0; j < 2; ++j) { const int i_ = 2 * (pp) + j; const unsigned off_ = (row0 + (i_ >> 2) * HALF + (i_ & 3) * 16) * 1024u + col; \
;                 xq[buf][j][0] = *(const f32x4*)(xin + off_); xq[buf][j][1] = *(const f32x4*)(xin + off_ + 4); } } while (0)
;     static __device__ __forceinline__ void run(const f32x4 (&acc)[2][2][4][2], const Unit& u, int wr, int wc, int fr, int fq, const float* xin, float* xout, const float* gate, float gs, const float* lazy_ssq, const float* lazy_g, ...
;     ...
;             constexpr bool DEEP = !LAZY && !WG2;
;             if (DEEP) RES_LD(0, 0);
; #pragma unroll
;             for (int pp = 0; pp < 4; ++pp) {
;                 if (DEEP) { if (pp < 3) RES_LD((pp + 1) & 1, pp + 1); } else RES_LD(pp & 1, pp);
; #pragma unroll
;                 for (int j = 0; j < 2; ++j) { const int i_ = 2 * pp + j, ai = i_ >> 2, m = i_ & 3; const unsigned off = (row0 + ai * HALF + m * 16) * 1024u + col;
;                     const f32x4 xi0 = xq[pp & 1][j][0], xi1 = xq[pp & 1][j][1];
;                     f32x4 xo0 = gv[0] * acc[ai][bj][m][0], xo1 = gv[1] * acc[ai][bj][m][1];
;                     if (LAZY) { xo0 = xo0 + xi0 * lg[0] * rl[ai][m]; xo1 = xo1 + xi1 * lg[1] * rl[ai][m]; } else { xo0 = xo0 + xi0; xo1 = xo1 + xi1; }
;                     *(f32x4*)(xout + off) = xo0; *(f32x4*)(xout + off + 4) = xo1;
;                     if (aout) { const f32x4 a0 = xo0 * wv[0], a1 = xo1 * wv[1]; u32x4 w; w.x = cvt_pk_bf16(a0[0], a0[1]); w.y = cvt_pk_bf16(a0[2], a0[3]); w.z = cvt_pk_bf16(a1[0], a1[1]); w.w = cvt_pk_bf16(a1[2], a1[3]);
;                         *(u32x4*)(aout + off) = w;
;                         sq[ai][m] += ((xo0[0] * xo0[0] + xo0[1] * xo0[1]) + (xo0[2] * xo0[2] + xo0[3] * xo0[3])) + ((xo1[0] * xo1[0] + xo1[1] * xo1[1]) + (xo1[2] * xo1[2] + xo1[3] * xo1[3]));
;                         if (WG2) { const f32x4 b0 = xo0 * w2[0], b1 = xo1 * w2[1]; sqb[ai][m] += ((b0[0] * b0[0] + b0[1] * b0[1]) + (b0[2] * b0[2] + b0[3] * b0[3])) + ((b1[0] * b1[0] + b1[1] * b1[1]) + (b1[2] * b1[2] + b1[3] * b1[3])); } } }
.LBB0_343:
	v_add_u32_e32 v196, 0x8000, v176
	v_mov_b32_e32 v197, v177
	v_lshlrev_b64 v[200:201], 2, v[196:197]
	v_lshl_add_u64 v[136:137], s[34:35], 0, v[200:201]
	global_load_dwordx4 v[144:147], v[136:137], off
	global_load_dwordx4 v[148:151], v[136:137], off offset:16
	v_add_u32_e32 v174, 0xc000, v176
	v_mov_b32_e32 v175, v177
	v_lshl_add_u64 v[140:141], v[174:175], 2, s[34:35]
	global_load_dwordx4 v[136:139], v[140:141], off offset:16
	s_nop 0
	global_load_dwordx4 v[140:143], v[140:141], off
	v_mov_b32_e32 v191, v190
	v_mov_b32_e32 v204, v190
	v_mov_b32_e32 v205, v190
	s_and_b64 vcc, exec, s[8:9]
	v_lshl_add_u64 v[200:201], s[30:31], 0, v[200:201]
	s_waitcnt vmcnt(0)
	v_pk_mul_f32 v[146:147], v[130:131], v[146:147]
	v_pk_mul_f32 v[144:145], v[128:129], v[144:145]
	s_waitcnt vmcnt(0)
	v_pk_mul_f32 v[150:151], v[134:135], v[150:151]
	v_pk_mul_f32 v[148:149], v[132:133], v[148:149]
	v_pk_mul_f32 v[146:147], v[204:205], v[146:147]
	v_pk_mul_f32 v[144:145], v[190:191], v[144:145]
	v_pk_mul_f32 v[204:205], v[204:205], v[150:151]
	v_pk_mul_f32 v[190:191], v[190:191], v[148:149]
	v_pk_fma_f32 v[150:151], v[86:87], v[194:195], v[146:147]
	v_pk_fma_f32 v[148:149], v[84:85], v[198:199], v[144:145]
	v_pk_fma_f32 v[146:147], v[82:83], v[182:183], v[204:205]
	v_pk_fma_f32 v[144:145], v[80:81], v[192:193], v[190:191]
	global_store_dwordx4 v[200:201], v[148:151], off
	global_store_dwordx4 v[200:201], v[144:147], off offset:16
	s_cbranch_vccnz .LBB0_345
	v_pk_mul_f32 v[190:191], v[188:189], v[150:151]
	v_pk_mul_f32 v[200:201], v[186:187], v[148:149]
	v_pk_mul_f32 v[242:243], v[184:185], v[144:145]
	v_cvt_pk_bf16_f32 v240, v200, v201
	v_cvt_pk_bf16_f32 v241, v190, v191
	v_lshl_add_u64 v[190:191], v[196:197], 1, s[28:29]
	v_pk_mul_f32 v[204:205], v[180:181], v[146:147]
	v_cvt_pk_bf16_f32 v242, v242, v243
	s_nop 0
	v_cvt_pk_bf16_f32 v243, v204, v205
	global_store_dwordx4 v[190:191], v[240:243], off
	v_mov_b32_e32 v191, v144
	v_mov_b32_e32 v144, v149
	v_mov_b32_e32 v149, v146
	v_mov_b32_e32 v146, v151
	v_mov_b32_e32 v190, v148
	v_pk_mul_f32 v[144:145], v[144:145], v[144:145]
	v_mov_b32_e32 v148, v150
	v_pk_mul_f32 v[146:147], v[146:147], v[146:147]
	v_pk_fma_f32 v[144:145], v[190:191], v[190:191], v[144:145]
	v_pk_fma_f32 v[146:147], v[148:149], v[148:149], v[146:147]
	s_nop 0
	v_pk_add_f32 v[144:145], v[144:145], v[146:147]
	s_nop 0
	v_add_f32_e32 v144, v144, v145
	v_add_f32_e32 v234, v234, v144
.LBB0_345:
	v_mov_b32_e32 v211, v210
	s_waitcnt vmcnt(0)
	v_pk_mul_f32 v[142:143], v[130:131], v[142:143]
	v_pk_mul_f32 v[140:141], v[128:129], v[140:141]
	v_mov_b32_e32 v144, v210
	v_mov_b32_e32 v145, v210
	v_pk_mul_f32 v[138:139], v[134:135], v[138:139]
	v_pk_mul_f32 v[136:137], v[132:133], v[136:137]
	v_pk_mul_f32 v[142:143], v[144:145], v[142:143]
	v_pk_mul_f32 v[140:141], v[210:211], v[140:141]
	v_pk_mul_f32 v[138:139], v[144:145], v[138:139]
	v_pk_mul_f32 v[136:137], v[210:211], v[136:137]
	v_pk_fma_f32 v[142:143], v[70:71], v[194:195], v[142:143]
	v_pk_fma_f32 v[140:141], v[68:69], v[198:199], v[140:141]
	v_pk_fma_f32 v[138:139], v[66:67], v[182:183], v[138:139]
	v_pk_fma_f32 v[136:137], v[64:65], v[192:193], v[136:137]
	v_lshl_add_u64 v[144:145], v[174:175], 2, s[30:31]
	s_and_b64 vcc, exec, s[8:9]
	global_store_dwordx4 v[144:145], v[140:143], off
	global_store_dwordx4 v[144:145], v[136:139], off offset:16
	s_cbranch_vccnz .LBB0_347
	v_pk_mul_f32 v[146:147], v[188:189], v[142:143]
	v_pk_mul_f32 v[144:145], v[186:187], v[140:141]
	v_pk_mul_f32 v[148:149], v[180:181], v[138:139]
	v_pk_mul_f32 v[150:151], v[184:185], v[136:137]
	v_cvt_pk_bf16_f32 v144, v144, v145
	v_cvt_pk_bf16_f32 v145, v146, v147
	s_nop 0
	v_cvt_pk_bf16_f32 v146, v150, v151
	v_cvt_pk_bf16_f32 v147, v148, v149
	v_lshl_add_u64 v[148:149], v[174:175], 1, s[28:29]
	global_store_dwordx4 v[148:149], v[144:147], off
	s_nop 1
	v_mov_b32_e32 v145, v136
	v_mov_b32_e32 v136, v141
	v_mov_b32_e32 v141, v138
	v_mov_b32_e32 v138, v143
	v_mov_b32_e32 v144, v140
	v_pk_mul_f32 v[136:137], v[136:137], v[136:137]
	v_mov_b32_e32 v140, v142
	v_pk_mul_f32 v[138:139], v[138:139], v[138:139]
	v_pk_fma_f32 v[136:137], v[144:145], v[144:145], v[136:137]
	v_pk_fma_f32 v[138:139], v[140:141], v[140:141], v[138:139]
	s_nop 0
	v_pk_add_f32 v[136:137], v[136:137], v[138:139]
	s_nop 0
	v_add_f32_e32 v136, v136, v137
	v_add_f32_e32 v233, v233, v136
.LBB0_347:
	v_add_u32_e32 v174, v213, v202
	v_mov_b32_e32 v175, v177
	v_lshl_add_u64 v[136:137], v[174:175], 2, s[34:35]
	global_load_dwordx4 v[148:151], v[136:137], off offset:16
	global_load_dwordx4 v[144:147], v[136:137], off
	v_add_u32_e32 v136, 0x4000, v174
	v_mov_b32_e32 v137, v177
	v_lshl_add_u64 v[140:141], v[136:137], 2, s[34:35]
	global_load_dwordx4 v[136:139], v[140:141], off offset:16
	s_nop 0
	global_load_dwordx4 v[140:143], v[140:141], off
	v_mov_b32_e32 v207, v206
	v_mov_b32_e32 v196, v206
	v_mov_b32_e32 v197, v206
	v_add_u32_e32 v190, 0x20000, v176
	v_mov_b32_e32 v191, v177
	s_and_b64 vcc, exec, s[8:9]
	s_waitcnt vmcnt(0)
	v_pk_mul_f32 v[150:151], v[134:135], v[150:151]
	s_waitcnt vmcnt(0)
	v_pk_mul_f32 v[146:147], v[130:131], v[146:147]
	v_pk_mul_f32 v[144:145], v[128:129], v[144:145]
	v_pk_mul_f32 v[148:149], v[132:133], v[148:149]
	v_pk_mul_f32 v[146:147], v[196:197], v[146:147]
	v_pk_mul_f32 v[144:145], v[206:207], v[144:145]
	v_pk_mul_f32 v[150:151], v[196:197], v[150:151]
	v_pk_mul_f32 v[148:149], v[206:207], v[148:149]
	v_pk_fma_f32 v[146:147], v[54:55], v[194:195], v[146:147]
	v_pk_fma_f32 v[144:145], v[52:53], v[198:199], v[144:145]
	v_pk_fma_f32 v[150:151], v[50:51], v[182:183], v[150:151]
	v_pk_fma_f32 v[148:149], v[48:49], v[192:193], v[148:149]
	v_lshl_add_u64 v[196:197], v[190:191], 2, s[30:31]
	global_store_dwordx4 v[196:197], v[144:147], off
	global_store_dwordx4 v[196:197], v[148:151], off offset:16
	s_cbranch_vccnz .LBB0_349
	v_pk_mul_f32 v[200:201], v[186:187], v[144:145]
	v_pk_mul_f32 v[202:203], v[184:185], v[148:149]
	v_lshl_add_u64 v[190:191], v[190:191], 1, s[28:29]
	v_pk_mul_f32 v[196:197], v[188:189], v[146:147]
	v_pk_mul_f32 v[204:205], v[180:181], v[150:151]
	v_cvt_pk_bf16_f32 v200, v200, v201
	v_cvt_pk_bf16_f32 v201, v196, v197
	v_cvt_pk_bf16_f32 v202, v202, v203
	s_nop 0
	v_cvt_pk_bf16_f32 v203, v204, v205
	global_store_dwordx4 v[190:191], v[200:203], off
	v_mov_b32_e32 v191, v148
	v_mov_b32_e32 v148, v145
	v_mov_b32_e32 v190, v144
	v_pk_mul_f32 v[144:145], v[148:149], v[148:149]
	v_mov_b32_e32 v149, v150
	v_mov_b32_e32 v150, v147
	v_mov_b32_e32 v148, v146
	v_pk_mul_f32 v[146:147], v[150:151], v[150:151]
	v_pk_fma_f32 v[144:145], v[190:191], v[190:191], v[144:145]
	v_pk_fma_f32 v[146:147], v[148:149], v[148:149], v[146:147]
	s_nop 0
	v_pk_add_f32 v[144:145], v[144:145], v[146:147]
	s_nop 0
	v_add_f32_e32 v144, v144, v145
	v_add_f32_e32 v236, v236, v144
; __device__ __forceinline__ unsigned cvt_pk_bf16(float lo, float hi) { unsigned r; asm volatile("v_cvt_pk_bf16_f32 %0, %1, %2" : "=v"(r) : "v"(lo), "v"(hi)); return r; }
; #define RES_LD(buf, pp) do { _Pragma("unroll") for (int j = 0; j < 2; ++j) { const int i_ = 2 * (pp) + j; const unsigned off_ = (row0 + (i_ >> 2) * HALF + (i_ & 3) * 16) * 1024u + col; \
;                 xq[buf][j][0] = *(const f32x4*)(xin + off_); xq[buf][j][1] = *(const f32x4*)(xin + off_ + 4); } } while (0)
;     static __device__ __forceinline__ void run(const f32x4 (&acc)[2][2][4][2], const Unit& u, int wr, int wc, int fr, int fq, const float* xin, float* xout, const float* gate, float gs, const float* lazy_ssq, const float* lazy_g, ...
;     ...
;             constexpr bool DEEP = !LAZY && !WG2;
;             if (DEEP) RES_LD(0, 0);
; #pragma unroll
;             for (int pp = 0; pp < 4; ++pp) {
;                 if (DEEP) { if (pp < 3) RES_LD((pp + 1) & 1, pp + 1); } else RES_LD(pp & 1, pp);
; #pragma unroll
;                 for (int j = 0; j < 2; ++j) { const int i_ = 2 * pp + j, ai = i_ >> 2, m = i_ & 3; const unsigned off = (row0 + ai * HALF + m * 16) * 1024u + col;
;                     const f32x4 xi0 = xq[pp & 1][j][0], xi1 = xq[pp & 1][j][1];
;                     f32x4 xo0 = gv[0] * acc[ai][bj][m][0], xo1 = gv[1] * acc[ai][bj][m][1];
;                     if (LAZY) { xo0 = xo0 + xi0 * lg[0] * rl[ai][m]; xo1 = xo1 + xi1 * lg[1] * rl[ai][m]; } else { xo0 = xo0 + xi0; xo1 = xo1 + xi1; }
;                     *(f32x4*)(xout + off) = xo0; *(f32x4*)(xout + off + 4) = xo1;
;                     if (aout) { const f32x4 a0 = xo0 * wv[0], a1 = xo1 * wv[1]; u32x4 w; w.x = cvt_pk_bf16(a0[0], a0[1]); w.y = cvt_pk_bf16(a0[2], a0[3]); w.z = cvt_pk_bf16(a1[0], a1[1]); w.w = cvt_pk_bf16(a1[2], a1[3]);
;                         *(u32x4*)(aout + off) = w;
;                         sq[ai][m] += ((xo0[0] * xo0[0] + xo0[1] * xo0[1]) + (xo0[2] * xo0[2] + xo0[3] * xo0[3])) + ((xo1[0] * xo1[0] + xo1[1] * xo1[1]) + (xo1[2] * xo1[2] + xo1[3] * xo1[3]));
;                         if (WG2) { const f32x4 b0 = xo0 * w2[0], b1 = xo1 * w2[1]; sqb[ai][m] += ((b0[0] * b0[0] + b0[1] * b0[1]) + (b0[2] * b0[2] + b0[3] * b0[3])) + ((b1[0] * b1[0] + b1[1] * b1[1]) + (b1[2] * b1[2] + b1[3] * b1[3])); } } }
.LBB0_349:
	v_mov_b32_e32 v213, v212
	s_waitcnt vmcnt(0)
	v_pk_mul_f32 v[142:143], v[130:131], v[142:143]
	v_pk_mul_f32 v[140:141], v[128:129], v[140:141]
	v_mov_b32_e32 v146, v212
	v_mov_b32_e32 v147, v212
	v_pk_mul_f32 v[138:139], v[134:135], v[138:139]
	v_pk_mul_f32 v[136:137], v[132:133], v[136:137]
	v_add_u32_e32 v144, 0x24000, v176
	v_pk_mul_f32 v[142:143], v[146:147], v[142:143]
	v_pk_mul_f32 v[140:141], v[212:213], v[140:141]
	v_pk_mul_f32 v[138:139], v[146:147], v[138:139]
	v_pk_mul_f32 v[136:137], v[212:213], v[136:137]
	v_mov_b32_e32 v145, v177
	v_pk_fma_f32 v[142:143], v[38:39], v[194:195], v[142:143]
	v_pk_fma_f32 v[140:141], v[36:37], v[198:199], v[140:141]
	v_pk_fma_f32 v[138:139], v[34:35], v[182:183], v[138:139]
	v_pk_fma_f32 v[136:137], v[32:33], v[192:193], v[136:137]
	v_lshl_add_u64 v[146:147], v[144:145], 2, s[30:31]
	s_and_b64 vcc, exec, s[8:9]
	global_store_dwordx4 v[146:147], v[140:143], off
	global_store_dwordx4 v[146:147], v[136:139], off offset:16
	s_cbranch_vccnz .LBB0_351
	v_pk_mul_f32 v[148:149], v[188:189], v[142:143]
	v_pk_mul_f32 v[146:147], v[186:187], v[140:141]
	v_lshl_add_u64 v[144:145], v[144:145], 1, s[28:29]
	v_pk_mul_f32 v[150:151], v[180:181], v[138:139]
	v_pk_mul_f32 v[190:191], v[184:185], v[136:137]
	v_cvt_pk_bf16_f32 v146, v146, v147
	v_cvt_pk_bf16_f32 v147, v148, v149
	s_nop 0
	v_cvt_pk_bf16_f32 v148, v190, v191
	v_cvt_pk_bf16_f32 v149, v150, v151
	global_store_dwordx4 v[144:145], v[146:149], off
	v_mov_b32_e32 v145, v136
	v_mov_b32_e32 v136, v141
	v_mov_b32_e32 v141, v138
	v_mov_b32_e32 v138, v143
	v_mov_b32_e32 v144, v140
	v_pk_mul_f32 v[136:137], v[136:137], v[136:137]
	v_mov_b32_e32 v140, v142
	v_pk_mul_f32 v[138:139], v[138:139], v[138:139]
	v_pk_fma_f32 v[136:137], v[144:145], v[144:145], v[136:137]
	v_pk_fma_f32 v[138:139], v[140:141], v[140:141], v[138:139]
	s_nop 0
	v_pk_add_f32 v[136:137], v[136:137], v[138:139]
	s_nop 0
	v_add_f32_e32 v136, v136, v137
	v_add_f32_e32 v235, v235, v136
.LBB0_351:
	s_nop 0
	v_add_u32_e32 v136, 0x8000, v174
	v_mov_b32_e32 v137, v177
	v_lshl_add_u64 v[136:137], v[136:137], 2, s[34:35]
	global_load_dwordx4 v[148:151], v[136:137], off offset:16
	global_load_dwordx4 v[144:147], v[136:137], off
	v_add_u32_e32 v136, 0xc000, v174
	v_mov_b32_e32 v137, v177
	v_lshl_add_u64 v[140:141], v[136:137], 2, s[34:35]
	global_load_dwordx4 v[136:139], v[140:141], off offset:16
	s_nop 0
	global_load_dwordx4 v[140:143], v[140:141], off
	v_mov_b32_e32 v209, v208
	v_mov_b32_e32 v190, v208
	v_mov_b32_e32 v191, v208
	v_add_u32_e32 v174, 0x28000, v176
	v_mov_b32_e32 v175, v177
	s_and_b64 vcc, exec, s[8:9]
	s_waitcnt vmcnt(0)
	v_pk_mul_f32 v[150:151], v[134:135], v[150:151]
	s_waitcnt vmcnt(0)
	v_pk_mul_f32 v[146:147], v[130:131], v[146:147]
	v_pk_mul_f32 v[144:145], v[128:129], v[144:145]
	v_pk_mul_f32 v[148:149], v[132:133], v[148:149]
	v_pk_mul_f32 v[146:147], v[190:191], v[146:147]
	v_pk_mul_f32 v[144:145], v[208:209], v[144:145]
	v_pk_mul_f32 v[150:151], v[190:191], v[150:151]
	v_pk_mul_f32 v[148:149], v[208:209], v[148:149]
	v_pk_fma_f32 v[146:147], v[22:23], v[194:195], v[146:147]
	v_pk_fma_f32 v[144:145], v[20:21], v[198:199], v[144:145]
	v_pk_fma_f32 v[150:151], v[18:19], v[182:183], v[150:151]
	v_pk_fma_f32 v[148:149], v[16:17], v[192:193], v[148:149]
	v_lshl_add_u64 v[190:191], v[174:175], 2, s[30:31]
	global_store_dwordx4 v[190:191], v[144:147], off
	global_store_dwordx4 v[190:191], v[148:151], off offset:16
	s_cbranch_vccnz .LBB0_353
	v_pk_mul_f32 v[202:203], v[184:185], v[148:149]
	v_lshl_add_u64 v[174:175], v[174:175], 1, s[28:29]
	v_pk_mul_f32 v[190:191], v[188:189], v[146:147]
	v_pk_mul_f32 v[196:197], v[186:187], v[144:145]
	v_pk_mul_f32 v[204:205], v[180:181], v[150:151]
	v_cvt_pk_bf16_f32 v200, v196, v197
	v_cvt_pk_bf16_f32 v201, v190, v191
	v_cvt_pk_bf16_f32 v202, v202, v203
	s_nop 0
	v_cvt_pk_bf16_f32 v203, v204, v205
	global_store_dwordx4 v[174:175], v[200:203], off
	v_mov_b32_e32 v175, v148
	v_mov_b32_e32 v148, v145
	v_mov_b32_e32 v174, v144
	v_pk_mul_f32 v[144:145], v[148:149], v[148:149]
	v_mov_b32_e32 v149, v150
	v_mov_b32_e32 v150, v147
	v_mov_b32_e32 v148, v146
	v_pk_mul_f32 v[146:147], v[150:151], v[150:151]
	v_pk_fma_f32 v[144:145], v[174:175], v[174:175], v[144:145]
	v_pk_fma_f32 v[146:147], v[148:149], v[148:149], v[146:147]
	s_nop 0
	v_pk_add_f32 v[144:145], v[144:145], v[146:147]
	s_nop 0
	v_add_f32_e32 v144, v144, v145
	v_add_f32_e32 v238, v238, v144
.LBB0_353:
	v_mov_b32_e32 v215, v214
	s_waitcnt vmcnt(0)
	v_pk_mul_f32 v[130:131], v[130:131], v[142:143]
	v_pk_mul_f32 v[128:129], v[128:129], v[140:141]
	v_mov_b32_e32 v140, v214
	v_mov_b32_e32 v141, v214
	v_pk_mul_f32 v[134:135], v[134:135], v[138:139]
	v_pk_mul_f32 v[132:133], v[132:133], v[136:137]
	v_add_u32_e32 v176, 0x2c000, v176
	v_pk_mul_f32 v[130:131], v[140:141], v[130:131]
	v_pk_mul_f32 v[128:129], v[214:215], v[128:129]
	v_pk_mul_f32 v[134:135], v[140:141], v[134:135]
	v_pk_mul_f32 v[132:133], v[214:215], v[132:133]
	v_pk_fma_f32 v[130:131], v[6:7], v[194:195], v[130:131]
	v_pk_fma_f32 v[128:129], v[4:5], v[198:199], v[128:129]
	v_pk_fma_f32 v[134:135], v[2:3], v[182:183], v[134:135]
	v_pk_fma_f32 v[132:133], v[0:1], v[192:193], v[132:133]
	v_lshl_add_u64 v[136:137], v[176:177], 2, s[30:31]
	s_and_b64 vcc, exec, s[8:9]
	global_store_dwordx4 v[136:137], v[128:131], off
	global_store_dwordx4 v[136:137], v[132:135], off offset:16
	s_cbranch_vccnz .LBB0_355
	v_pk_mul_f32 v[138:139], v[188:189], v[130:131]
	v_pk_mul_f32 v[136:137], v[186:187], v[128:129]
	v_pk_mul_f32 v[140:141], v[180:181], v[134:135]
	v_pk_mul_f32 v[142:143], v[184:185], v[132:133]
	v_cvt_pk_bf16_f32 v136, v136, v137
	v_cvt_pk_bf16_f32 v137, v138, v139
	s_nop 0
	v_cvt_pk_bf16_f32 v138, v142, v143
	v_cvt_pk_bf16_f32 v139, v140, v141
	v_lshl_add_u64 v[140:141], v[176:177], 1, s[28:29]
	global_store_dwordx4 v[140:141], v[136:139], off
	s_nop 1
	v_mov_b32_e32 v137, v132
	v_mov_b32_e32 v132, v129
	v_mov_b32_e32 v136, v128
	v_pk_mul_f32 v[128:129], v[132:133], v[132:133]
	v_mov_b32_e32 v133, v134
	v_mov_b32_e32 v134, v131
	v_mov_b32_e32 v132, v130
	v_pk_mul_f32 v[130:131], v[134:135], v[134:135]
	v_pk_fma_f32 v[128:129], v[136:137], v[136:137], v[128:129]
	v_pk_fma_f32 v[130:131], v[132:133], v[132:133], v[130:131]
	s_nop 0
	v_pk_add_f32 v[128:129], v[128:129], v[130:131]
	s_nop 0
	v_add_f32_e32 v128, v128, v129
	v_add_f32_e32 v237, v237, v128

; __device__ __forceinline__ unsigned cvt_pk_bf16(float lo, float hi) { unsigned r; asm volatile("v_cvt_pk_bf16_f32 %0, %1, %2" : "=v"(r) : "v"(lo), "v"(hi)); return r; }
; #define RES_LD(buf, pp) do { _Pragma("unroll") for (int j = 0; j < 2; ++j) { const int i_ = 2 * (pp) + j; const unsigned off_ = (row0 + (i_ >> 2) * HALF + (i_ & 3) * 16) * 1024u + col; \
;                 xq[buf][j][0] = *(const f32x4*)(xin + off_); xq[buf][j][1] = *(const f32x4*)(xin + off_ + 4); } } while (0)
;     static __device__ __forceinline__ void run(const f32x4 (&acc)[2][2][4][2], const Unit& u, int wr, int wc, int fr, int fq, const float* xin, float* xout, const float* gate, float gs, const float* lazy_ssq, const float* lazy_g, ...
;     ...
;             constexpr bool DEEP = !LAZY && !WG2;
;             if (DEEP) RES_LD(0, 0);
; #pragma unroll
;             for (int pp = 0; pp < 4; ++pp) {
;                 if (DEEP) { if (pp < 3) RES_LD((pp + 1) & 1, pp + 1); } else RES_LD(pp & 1, pp);
; #pragma unroll
;                 for (int j = 0; j < 2; ++j) { const int i_ = 2 * pp + j, ai = i_ >> 2, m = i_ & 3; const unsigned off = (row0 + ai * HALF + m * 16) * 1024u + col;
;                     const f32x4 xi0 = xq[pp & 1][j][0], xi1 = xq[pp & 1][j][1];
;                     f32x4 xo0 = gv[0] * acc[ai][bj][m][0], xo1 = gv[1] * acc[ai][bj][m][1];
;                     if (LAZY) { xo0 = xo0 + xi0 * lg[0] * rl[ai][m]; xo1 = xo1 + xi1 * lg[1] * rl[ai][m]; } else { xo0 = xo0 + xi0; xo1 = xo1 + xi1; }
;                     *(f32x4*)(xout + off) = xo0; *(f32x4*)(xout + off + 4) = xo1;
;                     if (aout) { const f32x4 a0 = xo0 * wv[0], a1 = xo1 * wv[1]; u32x4 w; w.x = cvt_pk_bf16(a0[0], a0[1]); w.y = cvt_pk_bf16(a0[2], a0[3]); w.z = cvt_pk_bf16(a1[0], a1[1]); w.w = cvt_pk_bf16(a1[2], a1[3]);
;                         *(u32x4*)(aout + off) = w;
;                         sq[ai][m] += ((xo0[0] * xo0[0] + xo0[1] * xo0[1]) + (xo0[2] * xo0[2] + xo0[3] * xo0[3])) + ((xo1[0] * xo1[0] + xo1[1] * xo1[1]) + (xo1[2] * xo1[2] + xo1[3] * xo1[3]));
;                         if (WG2) { const f32x4 b0 = xo0 * w2[0], b1 = xo1 * w2[1]; sqb[ai][m] += ((b0[0] * b0[0] + b0[1] * b0[1]) + (b0[2] * b0[2] + b0[3] * b0[3])) + ((b1[0] * b1[0] + b1[1] * b1[1]) + (b1[2] * b1[2] + b1[3] * b1[3])); } } }
.LBB0_387:
	v_add_u32_e32 v158, 0x8000, v176
	v_mov_b32_e32 v159, v177
	v_lshlrev_b64 v[148:149], 2, v[158:159]
	v_lshl_add_u64 v[136:137], s[38:39], 0, v[148:149]
	v_add_u32_e32 v172, 0xc000, v176
	v_mov_b32_e32 v173, v177
	global_load_dwordx4 v[144:147], v[136:137], off
	global_load_dwordx4 v[180:183], v[136:137], off offset:16
	v_lshl_add_u64 v[140:141], v[172:173], 2, s[38:39]
	global_load_dwordx4 v[136:139], v[140:141], off offset:16
	s_nop 0
	global_load_dwordx4 v[140:143], v[140:141], off
	s_and_b64 vcc, exec, s[8:9]
	v_lshl_add_u64 v[174:175], s[36:37], 0, v[148:149]
	s_waitcnt vmcnt(0)
	v_pk_fma_f32 v[150:151], v[94:95], v[204:205], v[146:147]
	v_pk_fma_f32 v[148:149], v[92:93], v[206:207], v[144:145]
	s_waitcnt vmcnt(0)
	v_pk_fma_f32 v[146:147], v[90:91], v[202:203], v[182:183]
	v_pk_fma_f32 v[144:145], v[88:89], v[200:201], v[180:181]
	global_store_dwordx4 v[174:175], v[148:151], off
	global_store_dwordx4 v[174:175], v[144:147], off offset:16
	s_cbranch_vccnz .LBB0_389
	v_pk_mul_f32 v[174:175], v[194:195], v[150:151]
	v_pk_mul_f32 v[180:181], v[186:187], v[148:149]
	v_pk_mul_f32 v[184:185], v[198:199], v[146:147]
	v_pk_mul_f32 v[182:183], v[196:197], v[144:145]
	v_cvt_pk_bf16_f32 v180, v180, v181
	v_cvt_pk_bf16_f32 v181, v174, v175
	v_lshl_add_u64 v[158:159], v[158:159], 1, s[34:35]
	v_pk_mul_f32 v[174:175], v[132:133], v[148:149]
	v_cvt_pk_bf16_f32 v182, v182, v183
	v_cvt_pk_bf16_f32 v183, v184, v185
	global_store_dwordx4 v[158:159], v[180:183], off
	v_pk_mul_f32 v[158:159], v[134:135], v[150:151]
	v_mov_b32_e32 v185, v174
	v_mov_b32_e32 v174, v149
	v_mov_b32_e32 v184, v148
	v_pk_mul_f32 v[148:149], v[174:175], v[174:175]
	v_mov_b32_e32 v175, v158
	v_mov_b32_e32 v158, v151
	v_mov_b32_e32 v174, v150
	v_pk_mul_f32 v[150:151], v[158:159], v[158:159]
	v_pk_mul_f32 v[182:183], v[128:129], v[144:145]
	v_pk_fma_f32 v[148:149], v[184:185], v[184:185], v[148:149]
	v_pk_fma_f32 v[150:151], v[174:175], v[174:175], v[150:151]
	v_pk_mul_f32 v[180:181], v[130:131], v[146:147]
	v_pk_add_f32 v[148:149], v[148:149], v[150:151]
	v_mov_b32_e32 v151, v182
	v_mov_b32_e32 v182, v145
	v_mov_b32_e32 v150, v144
	v_pk_mul_f32 v[144:145], v[182:183], v[182:183]
	s_nop 0
	v_pk_fma_f32 v[144:145], v[150:151], v[150:151], v[144:145]
	v_mov_b32_e32 v151, v180
	v_mov_b32_e32 v180, v147
	v_mov_b32_e32 v150, v146
	v_pk_mul_f32 v[146:147], v[180:181], v[180:181]
	s_nop 0
	v_pk_fma_f32 v[146:147], v[150:151], v[150:151], v[146:147]
	s_nop 0
	v_pk_add_f32 v[144:145], v[144:145], v[146:147]
	s_nop 0
	v_pk_add_f32 v[158:159], v[148:149], v[144:145]
	s_branch .LBB0_390

; __device__ __forceinline__ unsigned cvt_pk_bf16(float lo, float hi) { unsigned r; asm volatile("v_cvt_pk_bf16_f32 %0, %1, %2" : "=v"(r) : "v"(lo), "v"(hi)); return r; }
; #define RES_LD(buf, pp) do { _Pragma("unroll") for (int j = 0; j < 2; ++j) { const int i_ = 2 * (pp) + j; const unsigned off_ = (row0 + (i_ >> 2) * HALF + (i_ & 3) * 16) * 1024u + col; \
;                 xq[buf][j][0] = *(const f32x4*)(xin + off_); xq[buf][j][1] = *(const f32x4*)(xin + off_ + 4); } } while (0)
;     static __device__ __forceinline__ void run(const f32x4 (&acc)[2][2][4][2], const Unit& u, int wr, int wc, int fr, int fq, const float* xin, float* xout, const float* gate, float gs, const float* lazy_ssq, const float* lazy_g, ...
;     ...
;             constexpr bool DEEP = !LAZY && !WG2;
;             if (DEEP) RES_LD(0, 0);
; #pragma unroll
;             for (int pp = 0; pp < 4; ++pp) {
;                 if (DEEP) { if (pp < 3) RES_LD((pp + 1) & 1, pp + 1); } else RES_LD(pp & 1, pp);
; #pragma unroll
;                 for (int j = 0; j < 2; ++j) { const int i_ = 2 * pp + j, ai = i_ >> 2, m = i_ & 3; const unsigned off = (row0 + ai * HALF + m * 16) * 1024u + col;
;                     const f32x4 xi0 = xq[pp & 1][j][0], xi1 = xq[pp & 1][j][1];
;                     f32x4 xo0 = gv[0] * acc[ai][bj][m][0], xo1 = gv[1] * acc[ai][bj][m][1];
;                     if (LAZY) { xo0 = xo0 + xi0 * lg[0] * rl[ai][m]; xo1 = xo1 + xi1 * lg[1] * rl[ai][m]; } else { xo0 = xo0 + xi0; xo1 = xo1 + xi1; }
;                     *(f32x4*)(xout + off) = xo0; *(f32x4*)(xout + off + 4) = xo1;
;                     if (aout) { const f32x4 a0 = xo0 * wv[0], a1 = xo1 * wv[1]; u32x4 w; w.x = cvt_pk_bf16(a0[0], a0[1]); w.y = cvt_pk_bf16(a0[2], a0[3]); w.z = cvt_pk_bf16(a1[0], a1[1]); w.w = cvt_pk_bf16(a1[2], a1[3]);
;                         *(u32x4*)(aout + off) = w;
;                         sq[ai][m] += ((xo0[0] * xo0[0] + xo0[1] * xo0[1]) + (xo0[2] * xo0[2] + xo0[3] * xo0[3])) + ((xo1[0] * xo1[0] + xo1[1] * xo1[1]) + (xo1[2] * xo1[2] + xo1[3] * xo1[3]));
;                         if (WG2) { const f32x4 b0 = xo0 * w2[0], b1 = xo1 * w2[1]; sqb[ai][m] += ((b0[0] * b0[0] + b0[1] * b0[1]) + (b0[2] * b0[2] + b0[3] * b0[3])) + ((b1[0] * b1[0] + b1[1] * b1[1]) + (b1[2] * b1[2] + b1[3] * b1[3])); } } }
.LBB0_390:
	s_waitcnt vmcnt(0)
	v_pk_fma_f32 v[142:143], v[78:79], v[204:205], v[142:143]
	v_pk_fma_f32 v[140:141], v[76:77], v[206:207], v[140:141]
	v_pk_fma_f32 v[138:139], v[74:75], v[202:203], v[138:139]
	v_pk_fma_f32 v[136:137], v[72:73], v[200:201], v[136:137]
	v_lshl_add_u64 v[144:145], v[172:173], 2, s[36:37]
	s_and_b64 vcc, exec, s[8:9]
	global_store_dwordx4 v[144:145], v[140:143], off
	global_store_dwordx4 v[144:145], v[136:139], off offset:16
	s_cbranch_vccnz .LBB0_392
	v_pk_mul_f32 v[146:147], v[194:195], v[142:143]
	v_pk_mul_f32 v[144:145], v[186:187], v[140:141]
	v_pk_mul_f32 v[148:149], v[198:199], v[138:139]
	v_pk_mul_f32 v[150:151], v[196:197], v[136:137]
	v_cvt_pk_bf16_f32 v144, v144, v145
	v_cvt_pk_bf16_f32 v145, v146, v147
	s_nop 0
	v_cvt_pk_bf16_f32 v146, v150, v151
	v_cvt_pk_bf16_f32 v147, v148, v149
	v_lshl_add_u64 v[148:149], v[172:173], 1, s[34:35]
	global_store_dwordx4 v[148:149], v[144:147], off
	v_mov_b32_e32 v172, v140
	v_pk_mul_f32 v[150:151], v[128:129], v[136:137]
	v_pk_mul_f32 v[146:147], v[132:133], v[140:141]
	v_pk_mul_f32 v[144:145], v[134:135], v[142:143]
	v_mov_b32_e32 v173, v146
	v_mov_b32_e32 v146, v141
	v_pk_mul_f32 v[140:141], v[146:147], v[146:147]
	v_mov_b32_e32 v147, v144
	v_mov_b32_e32 v144, v143
	v_mov_b32_e32 v146, v142
	v_pk_mul_f32 v[142:143], v[144:145], v[144:145]
	v_pk_fma_f32 v[140:141], v[172:173], v[172:173], v[140:141]
	v_pk_fma_f32 v[142:143], v[146:147], v[146:147], v[142:143]
	v_pk_mul_f32 v[148:149], v[130:131], v[138:139]
	v_pk_add_f32 v[140:141], v[140:141], v[142:143]
	v_mov_b32_e32 v143, v150
	v_mov_b32_e32 v150, v137
	v_mov_b32_e32 v142, v136
	v_pk_mul_f32 v[136:137], v[150:151], v[150:151]
	s_nop 0
	v_pk_fma_f32 v[136:137], v[142:143], v[142:143], v[136:137]
	v_mov_b32_e32 v143, v148
	v_mov_b32_e32 v148, v139
	v_mov_b32_e32 v142, v138
	v_pk_mul_f32 v[138:139], v[148:149], v[148:149]
	s_nop 0
	v_pk_fma_f32 v[138:139], v[142:143], v[142:143], v[138:139]
	s_nop 0
	v_pk_add_f32 v[136:137], v[136:137], v[138:139]
	s_nop 0
	v_pk_add_f32 v[174:175], v[140:141], v[136:137]
	s_branch .LBB0_393

; __device__ __forceinline__ unsigned cvt_pk_bf16(float lo, float hi) { unsigned r; asm volatile("v_cvt_pk_bf16_f32 %0, %1, %2" : "=v"(r) : "v"(lo), "v"(hi)); return r; }
; #define RES_LD(buf, pp) do { _Pragma("unroll") for (int j = 0; j < 2; ++j) { const int i_ = 2 * (pp) + j; const unsigned off_ = (row0 + (i_ >> 2) * HALF + (i_ & 3) * 16) * 1024u + col; \
;                 xq[buf][j][0] = *(const f32x4*)(xin + off_); xq[buf][j][1] = *(const f32x4*)(xin + off_ + 4); } } while (0)
;     static __device__ __forceinline__ void run(const f32x4 (&acc)[2][2][4][2], const Unit& u, int wr, int wc, int fr, int fq, const float* xin, float* xout, const float* gate, float gs, const float* lazy_ssq, const float* lazy_g, ...
;     ...
;             constexpr bool DEEP = !LAZY && !WG2;
;             if (DEEP) RES_LD(0, 0);
; #pragma unroll
;             for (int pp = 0; pp < 4; ++pp) {
;                 if (DEEP) { if (pp < 3) RES_LD((pp + 1) & 1, pp + 1); } else RES_LD(pp & 1, pp);
; #pragma unroll
;                 for (int j = 0; j < 2; ++j) { const int i_ = 2 * pp + j, ai = i_ >> 2, m = i_ & 3; const unsigned off = (row0 + ai * HALF + m * 16) * 1024u + col;
;                     const f32x4 xi0 = xq[pp & 1][j][0], xi1 = xq[pp & 1][j][1];
;                     f32x4 xo0 = gv[0] * acc[ai][bj][m][0], xo1 = gv[1] * acc[ai][bj][m][1];
;                     if (LAZY) { xo0 = xo0 + xi0 * lg[0] * rl[ai][m]; xo1 = xo1 + xi1 * lg[1] * rl[ai][m]; } else { xo0 = xo0 + xi0; xo1 = xo1 + xi1; }
;                     *(f32x4*)(xout + off) = xo0; *(f32x4*)(xout + off + 4) = xo1;
;                     if (aout) { const f32x4 a0 = xo0 * wv[0], a1 = xo1 * wv[1]; u32x4 w; w.x = cvt_pk_bf16(a0[0], a0[1]); w.y = cvt_pk_bf16(a0[2], a0[3]); w.z = cvt_pk_bf16(a1[0], a1[1]); w.w = cvt_pk_bf16(a1[2], a1[3]);
;                         *(u32x4*)(aout + off) = w;
;                         sq[ai][m] += ((xo0[0] * xo0[0] + xo0[1] * xo0[1]) + (xo0[2] * xo0[2] + xo0[3] * xo0[3])) + ((xo1[0] * xo1[0] + xo1[1] * xo1[1]) + (xo1[2] * xo1[2] + xo1[3] * xo1[3]));
;                         if (WG2) { const f32x4 b0 = xo0 * w2[0], b1 = xo1 * w2[1]; sqb[ai][m] += ((b0[0] * b0[0] + b0[1] * b0[1]) + (b0[2] * b0[2] + b0[3] * b0[3])) + ((b1[0] * b1[0] + b1[1] * b1[1]) + (b1[2] * b1[2] + b1[3] * b1[3])); } } }
.LBB0_393:
	v_add_u32_e32 v172, 0x80, v152
	v_lshlrev_b32_e32 v173, 10, v172
	v_add_u32_e32 v184, v173, v192
	v_mov_b32_e32 v185, v177
	v_lshl_add_u64 v[136:137], v[184:185], 2, s[38:39]
	global_load_dwordx4 v[144:147], v[136:137], off offset:16
	global_load_dwordx4 v[148:151], v[136:137], off
	v_add_u32_e32 v136, 0x4000, v184
	v_mov_b32_e32 v137, v177
	v_lshl_add_u64 v[140:141], v[136:137], 2, s[38:39]
	global_load_dwordx4 v[136:139], v[140:141], off offset:16
	s_nop 0
	global_load_dwordx4 v[140:143], v[140:141], off
	v_add_u32_e32 v180, 0x20000, v176
	v_mov_b32_e32 v181, v177
	v_lshl_add_u64 v[182:183], v[180:181], 2, s[36:37]
	s_and_b64 vcc, exec, s[8:9]
	s_waitcnt vmcnt(0)
	v_pk_fma_f32 v[146:147], v[58:59], v[202:203], v[146:147]
	s_waitcnt vmcnt(0)
	v_pk_fma_f32 v[150:151], v[62:63], v[204:205], v[150:151]
	v_pk_fma_f32 v[148:149], v[60:61], v[206:207], v[148:149]
	v_pk_fma_f32 v[144:145], v[56:57], v[200:201], v[144:145]
	global_store_dwordx4 v[182:183], v[148:151], off
	global_store_dwordx4 v[182:183], v[144:147], off offset:16
	s_cbranch_vccnz .LBB0_395
	v_pk_mul_f32 v[182:183], v[194:195], v[150:151]
	v_pk_mul_f32 v[208:209], v[186:187], v[148:149]
	v_pk_mul_f32 v[212:213], v[198:199], v[146:147]
	v_pk_mul_f32 v[210:211], v[196:197], v[144:145]
	v_cvt_pk_bf16_f32 v208, v208, v209
	v_cvt_pk_bf16_f32 v209, v182, v183
	v_lshl_add_u64 v[180:181], v[180:181], 1, s[34:35]
	v_pk_mul_f32 v[182:183], v[132:133], v[148:149]
	v_cvt_pk_bf16_f32 v210, v210, v211
	v_cvt_pk_bf16_f32 v211, v212, v213
	global_store_dwordx4 v[180:181], v[208:211], off
	v_pk_mul_f32 v[180:181], v[134:135], v[150:151]
	v_mov_b32_e32 v213, v182
	v_mov_b32_e32 v182, v149
	v_mov_b32_e32 v212, v148
	v_pk_mul_f32 v[148:149], v[182:183], v[182:183]
	v_mov_b32_e32 v183, v180
	v_mov_b32_e32 v180, v151
	v_mov_b32_e32 v182, v150
	v_pk_mul_f32 v[150:151], v[180:181], v[180:181]
	v_pk_mul_f32 v[210:211], v[128:129], v[144:145]
	v_pk_fma_f32 v[148:149], v[212:213], v[212:213], v[148:149]
	v_pk_fma_f32 v[150:151], v[182:183], v[182:183], v[150:151]
	v_pk_mul_f32 v[208:209], v[130:131], v[146:147]
	v_pk_add_f32 v[148:149], v[148:149], v[150:151]
	v_mov_b32_e32 v151, v210
	v_mov_b32_e32 v210, v145
	v_mov_b32_e32 v150, v144
	v_pk_mul_f32 v[144:145], v[210:211], v[210:211]
	s_nop 0
	v_pk_fma_f32 v[144:145], v[150:151], v[150:151], v[144:145]
	v_mov_b32_e32 v151, v208
	v_mov_b32_e32 v208, v147
	v_mov_b32_e32 v150, v146
	v_pk_mul_f32 v[146:147], v[208:209], v[208:209]
	s_nop 0
	v_pk_fma_f32 v[146:147], v[150:151], v[150:151], v[146:147]
	s_nop 0
	v_pk_add_f32 v[144:145], v[144:145], v[146:147]
	s_nop 0
	v_pk_add_f32 v[180:181], v[148:149], v[144:145]
	s_branch .LBB0_396

; __device__ __forceinline__ unsigned cvt_pk_bf16(float lo, float hi) { unsigned r; asm volatile("v_cvt_pk_bf16_f32 %0, %1, %2" : "=v"(r) : "v"(lo), "v"(hi)); return r; }
; #define RES_LD(buf, pp) do { _Pragma("unroll") for (int j = 0; j < 2; ++j) { const int i_ = 2 * (pp) + j; const unsigned off_ = (row0 + (i_ >> 2) * HALF + (i_ & 3) * 16) * 1024u + col; \
;                 xq[buf][j][0] = *(const f32x4*)(xin + off_); xq[buf][j][1] = *(const f32x4*)(xin + off_ + 4); } } while (0)
;     static __device__ __forceinline__ void run(const f32x4 (&acc)[2][2][4][2], const Unit& u, int wr, int wc, int fr, int fq, const float* xin, float* xout, const float* gate, float gs, const float* lazy_ssq, const float* lazy_g, ...
;     ...
;             constexpr bool DEEP = !LAZY && !WG2;
;             if (DEEP) RES_LD(0, 0);
; #pragma unroll
;             for (int pp = 0; pp < 4; ++pp) {
;                 if (DEEP) { if (pp < 3) RES_LD((pp + 1) & 1, pp + 1); } else RES_LD(pp & 1, pp);
; #pragma unroll
;                 for (int j = 0; j < 2; ++j) { const int i_ = 2 * pp + j, ai = i_ >> 2, m = i_ & 3; const unsigned off = (row0 + ai * HALF + m * 16) * 1024u + col;
;                     const f32x4 xi0 = xq[pp & 1][j][0], xi1 = xq[pp & 1][j][1];
;                     f32x4 xo0 = gv[0] * acc[ai][bj][m][0], xo1 = gv[1] * acc[ai][bj][m][1];
;                     if (LAZY) { xo0 = xo0 + xi0 * lg[0] * rl[ai][m]; xo1 = xo1 + xi1 * lg[1] * rl[ai][m]; } else { xo0 = xo0 + xi0; xo1 = xo1 + xi1; }
;                     *(f32x4*)(xout + off) = xo0; *(f32x4*)(xout + off + 4) = xo1;
;                     if (aout) { const f32x4 a0 = xo0 * wv[0], a1 = xo1 * wv[1]; u32x4 w; w.x = cvt_pk_bf16(a0[0], a0[1]); w.y = cvt_pk_bf16(a0[2], a0[3]); w.z = cvt_pk_bf16(a1[0], a1[1]); w.w = cvt_pk_bf16(a1[2], a1[3]);
;                         *(u32x4*)(aout + off) = w;
;                         sq[ai][m] += ((xo0[0] * xo0[0] + xo0[1] * xo0[1]) + (xo0[2] * xo0[2] + xo0[3] * xo0[3])) + ((xo1[0] * xo1[0] + xo1[1] * xo1[1]) + (xo1[2] * xo1[2] + xo1[3] * xo1[3]));
;                         if (WG2) { const f32x4 b0 = xo0 * w2[0], b1 = xo1 * w2[1]; sqb[ai][m] += ((b0[0] * b0[0] + b0[1] * b0[1]) + (b0[2] * b0[2] + b0[3] * b0[3])) + ((b1[0] * b1[0] + b1[1] * b1[1]) + (b1[2] * b1[2] + b1[3] * b1[3])); } } }
.LBB0_396:
	v_add_u32_e32 v144, 0x24000, v176
	v_mov_b32_e32 v145, v177
	s_waitcnt vmcnt(0)
	v_pk_fma_f32 v[142:143], v[46:47], v[204:205], v[142:143]
	v_pk_fma_f32 v[140:141], v[44:45], v[206:207], v[140:141]
	v_pk_fma_f32 v[138:139], v[42:43], v[202:203], v[138:139]
	v_pk_fma_f32 v[136:137], v[40:41], v[200:201], v[136:137]
	v_lshl_add_u64 v[146:147], v[144:145], 2, s[36:37]
	s_and_b64 vcc, exec, s[8:9]
	global_store_dwordx4 v[146:147], v[140:143], off
	global_store_dwordx4 v[146:147], v[136:139], off offset:16
	s_cbranch_vccnz .LBB0_398
	v_pk_mul_f32 v[146:147], v[186:187], v[140:141]
	v_pk_mul_f32 v[148:149], v[194:195], v[142:143]
	v_cvt_pk_bf16_f32 v146, v146, v147
	v_lshl_add_u64 v[144:145], v[144:145], 1, s[34:35]
	v_cvt_pk_bf16_f32 v147, v148, v149
	v_pk_mul_f32 v[150:151], v[198:199], v[138:139]
	v_pk_mul_f32 v[182:183], v[196:197], v[136:137]
	s_nop 0
	v_cvt_pk_bf16_f32 v148, v182, v183
	v_cvt_pk_bf16_f32 v149, v150, v151
	global_store_dwordx4 v[144:145], v[146:149], off
	v_pk_mul_f32 v[144:145], v[134:135], v[142:143]
	v_mov_b32_e32 v182, v140
	v_pk_mul_f32 v[146:147], v[132:133], v[140:141]
	v_pk_mul_f32 v[150:151], v[128:129], v[136:137]
	v_mov_b32_e32 v183, v146
	v_mov_b32_e32 v146, v141
	v_pk_mul_f32 v[140:141], v[146:147], v[146:147]
	v_mov_b32_e32 v147, v144
	v_mov_b32_e32 v144, v143
	v_mov_b32_e32 v146, v142
	v_pk_mul_f32 v[142:143], v[144:145], v[144:145]
	v_pk_fma_f32 v[140:141], v[182:183], v[182:183], v[140:141]
	v_pk_fma_f32 v[142:143], v[146:147], v[146:147], v[142:143]
	v_pk_mul_f32 v[148:149], v[130:131], v[138:139]
	v_pk_add_f32 v[140:141], v[140:141], v[142:143]
	v_mov_b32_e32 v143, v150
	v_mov_b32_e32 v150, v137
	v_mov_b32_e32 v142, v136
	v_pk_mul_f32 v[136:137], v[150:151], v[150:151]
	s_nop 0
	v_pk_fma_f32 v[136:137], v[142:143], v[142:143], v[136:137]
	v_mov_b32_e32 v143, v148
	v_mov_b32_e32 v148, v139
	v_mov_b32_e32 v142, v138
	v_pk_mul_f32 v[138:139], v[148:149], v[148:149]
	s_nop 0
	v_pk_fma_f32 v[138:139], v[142:143], v[142:143], v[138:139]
	s_nop 0
	v_pk_add_f32 v[136:137], v[136:137], v[138:139]
	s_nop 0
	v_pk_add_f32 v[182:183], v[140:141], v[136:137]
	s_branch .LBB0_399

; __device__ __forceinline__ unsigned cvt_pk_bf16(float lo, float hi) { unsigned r; asm volatile("v_cvt_pk_bf16_f32 %0, %1, %2" : "=v"(r) : "v"(lo), "v"(hi)); return r; }
; #define RES_LD(buf, pp) do { _Pragma("unroll") for (int j = 0; j < 2; ++j) { const int i_ = 2 * (pp) + j; const unsigned off_ = (row0 + (i_ >> 2) * HALF + (i_ & 3) * 16) * 1024u + col; \
;                 xq[buf][j][0] = *(const f32x4*)(xin + off_); xq[buf][j][1] = *(const f32x4*)(xin + off_ + 4); } } while (0)
;     static __device__ __forceinline__ void run(const f32x4 (&acc)[2][2][4][2], const Unit& u, int wr, int wc, int fr, int fq, const float* xin, float* xout, const float* gate, float gs, const float* lazy_ssq, const float* lazy_g, ...
;     ...
;             constexpr bool DEEP = !LAZY && !WG2;
;             if (DEEP) RES_LD(0, 0);
; #pragma unroll
;             for (int pp = 0; pp < 4; ++pp) {
;                 if (DEEP) { if (pp < 3) RES_LD((pp + 1) & 1, pp + 1); } else RES_LD(pp & 1, pp);
; #pragma unroll
;                 for (int j = 0; j < 2; ++j) { const int i_ = 2 * pp + j, ai = i_ >> 2, m = i_ & 3; const unsigned off = (row0 + ai * HALF + m * 16) * 1024u + col;
;                     const f32x4 xi0 = xq[pp & 1][j][0], xi1 = xq[pp & 1][j][1];
;                     f32x4 xo0 = gv[0] * acc[ai][bj][m][0], xo1 = gv[1] * acc[ai][bj][m][1];
;                     if (LAZY) { xo0 = xo0 + xi0 * lg[0] * rl[ai][m]; xo1 = xo1 + xi1 * lg[1] * rl[ai][m]; } else { xo0 = xo0 + xi0; xo1 = xo1 + xi1; }
;                     *(f32x4*)(xout + off) = xo0; *(f32x4*)(xout + off + 4) = xo1;
;                     if (aout) { const f32x4 a0 = xo0 * wv[0], a1 = xo1 * wv[1]; u32x4 w; w.x = cvt_pk_bf16(a0[0], a0[1]); w.y = cvt_pk_bf16(a0[2], a0[3]); w.z = cvt_pk_bf16(a1[0], a1[1]); w.w = cvt_pk_bf16(a1[2], a1[3]);
;                         *(u32x4*)(aout + off) = w;
;                         sq[ai][m] += ((xo0[0] * xo0[0] + xo0[1] * xo0[1]) + (xo0[2] * xo0[2] + xo0[3] * xo0[3])) + ((xo1[0] * xo1[0] + xo1[1] * xo1[1]) + (xo1[2] * xo1[2] + xo1[3] * xo1[3]));
;                         if (WG2) { const f32x4 b0 = xo0 * w2[0], b1 = xo1 * w2[1]; sqb[ai][m] += ((b0[0] * b0[0] + b0[1] * b0[1]) + (b0[2] * b0[2] + b0[3] * b0[3])) + ((b1[0] * b1[0] + b1[1] * b1[1]) + (b1[2] * b1[2] + b1[3] * b1[3])); } } }
.LBB0_399:
	v_add_u32_e32 v136, 0x8000, v184
	v_mov_b32_e32 v137, v177
	v_lshl_add_u64 v[136:137], v[136:137], 2, s[38:39]
	global_load_dwordx4 v[144:147], v[136:137], off offset:16
	global_load_dwordx4 v[148:151], v[136:137], off
	v_add_u32_e32 v136, 0xc000, v184
	v_mov_b32_e32 v137, v177
	v_lshl_add_u64 v[140:141], v[136:137], 2, s[38:39]
	global_load_dwordx4 v[136:139], v[140:141], off offset:16
	s_nop 0
	global_load_dwordx4 v[140:143], v[140:141], off
	v_add_u32_e32 v184, 0x28000, v176
	v_mov_b32_e32 v185, v177
	v_lshl_add_u64 v[208:209], v[184:185], 2, s[36:37]
	s_and_b64 vcc, exec, s[8:9]
	s_waitcnt vmcnt(0)
	v_pk_fma_f32 v[146:147], v[26:27], v[202:203], v[146:147]
	s_waitcnt vmcnt(0)
	v_pk_fma_f32 v[150:151], v[30:31], v[204:205], v[150:151]
	v_pk_fma_f32 v[148:149], v[28:29], v[206:207], v[148:149]
	v_pk_fma_f32 v[144:145], v[24:25], v[200:201], v[144:145]
	global_store_dwordx4 v[208:209], v[148:151], off
	global_store_dwordx4 v[208:209], v[144:147], off offset:16
	s_cbranch_vccnz .LBB0_401
	v_pk_mul_f32 v[208:209], v[186:187], v[148:149]
	v_pk_mul_f32 v[210:211], v[194:195], v[150:151]
	v_cvt_pk_bf16_f32 v208, v208, v209
	v_lshl_add_u64 v[184:185], v[184:185], 1, s[34:35]
	v_cvt_pk_bf16_f32 v209, v210, v211
	v_pk_mul_f32 v[212:213], v[198:199], v[146:147]
	v_pk_mul_f32 v[214:215], v[196:197], v[144:145]
	s_nop 0
	v_cvt_pk_bf16_f32 v210, v214, v215
	v_cvt_pk_bf16_f32 v211, v212, v213
	global_store_dwordx4 v[184:185], v[208:211], off
	v_pk_mul_f32 v[184:185], v[134:135], v[150:151]
	v_mov_b32_e32 v214, v148
	v_pk_mul_f32 v[208:209], v[132:133], v[148:149]
	v_pk_mul_f32 v[212:213], v[128:129], v[144:145]
	v_mov_b32_e32 v215, v208
	v_mov_b32_e32 v208, v149
	v_pk_mul_f32 v[148:149], v[208:209], v[208:209]
	v_mov_b32_e32 v209, v184
	v_mov_b32_e32 v184, v151
	v_mov_b32_e32 v208, v150
	v_pk_mul_f32 v[150:151], v[184:185], v[184:185]
	v_pk_fma_f32 v[148:149], v[214:215], v[214:215], v[148:149]
	v_pk_fma_f32 v[150:151], v[208:209], v[208:209], v[150:151]
	v_pk_mul_f32 v[210:211], v[130:131], v[146:147]
	v_pk_add_f32 v[148:149], v[148:149], v[150:151]
	v_mov_b32_e32 v151, v212
	v_mov_b32_e32 v212, v145
	v_mov_b32_e32 v150, v144
	v_pk_mul_f32 v[144:145], v[212:213], v[212:213]
	s_nop 0
	v_pk_fma_f32 v[144:145], v[150:151], v[150:151], v[144:145]
	v_mov_b32_e32 v151, v210
	v_mov_b32_e32 v210, v147
	v_mov_b32_e32 v150, v146
	v_pk_mul_f32 v[146:147], v[210:211], v[210:211]
	s_nop 0
	v_pk_fma_f32 v[146:147], v[150:151], v[150:151], v[146:147]
	s_nop 0
	v_pk_add_f32 v[144:145], v[144:145], v[146:147]
	s_nop 0
	v_pk_add_f32 v[184:185], v[148:149], v[144:145]
	s_branch .LBB0_402

; __device__ __forceinline__ unsigned cvt_pk_bf16(float lo, float hi) { unsigned r; asm volatile("v_cvt_pk_bf16_f32 %0, %1, %2" : "=v"(r) : "v"(lo), "v"(hi)); return r; }
; #define RES_LD(buf, pp) do { _Pragma("unroll") for (int j = 0; j < 2; ++j) { const int i_ = 2 * (pp) + j; const unsigned off_ = (row0 + (i_ >> 2) * HALF + (i_ & 3) * 16) * 1024u + col; \
;                 xq[buf][j][0] = *(const f32x4*)(xin + off_); xq[buf][j][1] = *(const f32x4*)(xin + off_ + 4); } } while (0)
;     static __device__ __forceinline__ void run(const f32x4 (&acc)[2][2][4][2], const Unit& u, int wr, int wc, int fr, int fq, const float* xin, float* xout, const float* gate, float gs, const float* lazy_ssq, const float* lazy_g, ...
;     ...
;             constexpr bool DEEP = !LAZY && !WG2;
;             if (DEEP) RES_LD(0, 0);
; #pragma unroll
;             for (int pp = 0; pp < 4; ++pp) {
;                 if (DEEP) { if (pp < 3) RES_LD((pp + 1) & 1, pp + 1); } else RES_LD(pp & 1, pp);
; #pragma unroll
;                 for (int j = 0; j < 2; ++j) { const int i_ = 2 * pp + j, ai = i_ >> 2, m = i_ & 3; const unsigned off = (row0 + ai * HALF + m * 16) * 1024u + col;
;                     const f32x4 xi0 = xq[pp & 1][j][0], xi1 = xq[pp & 1][j][1];
;                     f32x4 xo0 = gv[0] * acc[ai][bj][m][0], xo1 = gv[1] * acc[ai][bj][m][1];
;                     if (LAZY) { xo0 = xo0 + xi0 * lg[0] * rl[ai][m]; xo1 = xo1 + xi1 * lg[1] * rl[ai][m]; } else { xo0 = xo0 + xi0; xo1 = xo1 + xi1; }
;                     *(f32x4*)(xout + off) = xo0; *(f32x4*)(xout + off + 4) = xo1;
;                     if (aout) { const f32x4 a0 = xo0 * wv[0], a1 = xo1 * wv[1]; u32x4 w; w.x = cvt_pk_bf16(a0[0], a0[1]); w.y = cvt_pk_bf16(a0[2], a0[3]); w.z = cvt_pk_bf16(a1[0], a1[1]); w.w = cvt_pk_bf16(a1[2], a1[3]);
;                         *(u32x4*)(aout + off) = w;
;                         sq[ai][m] += ((xo0[0] * xo0[0] + xo0[1] * xo0[1]) + (xo0[2] * xo0[2] + xo0[3] * xo0[3])) + ((xo1[0] * xo1[0] + xo1[1] * xo1[1]) + (xo1[2] * xo1[2] + xo1[3] * xo1[3]));
;                         if (WG2) { const f32x4 b0 = xo0 * w2[0], b1 = xo1 * w2[1]; sqb[ai][m] += ((b0[0] * b0[0] + b0[1] * b0[1]) + (b0[2] * b0[2] + b0[3] * b0[3])) + ((b1[0] * b1[0] + b1[1] * b1[1]) + (b1[2] * b1[2] + b1[3] * b1[3])); } } }
.LBB0_402:
	v_add_u32_e32 v176, 0x2c000, v176
	s_waitcnt vmcnt(0)
	v_pk_fma_f32 v[142:143], v[14:15], v[204:205], v[142:143]
	v_pk_fma_f32 v[140:141], v[12:13], v[206:207], v[140:141]
	v_pk_fma_f32 v[138:139], v[10:11], v[202:203], v[138:139]
	v_pk_fma_f32 v[136:137], v[8:9], v[200:201], v[136:137]
	v_lshl_add_u64 v[144:145], v[176:177], 2, s[36:37]
	s_and_b64 vcc, exec, s[8:9]
	global_store_dwordx4 v[144:145], v[140:143], off
	global_store_dwordx4 v[144:145], v[136:139], off offset:16
	s_cbranch_vccnz .LBB0_404
	v_pk_mul_f32 v[146:147], v[194:195], v[142:143]
	v_pk_mul_f32 v[144:145], v[186:187], v[140:141]
	v_pk_mul_f32 v[148:149], v[198:199], v[138:139]
	v_pk_mul_f32 v[150:151], v[196:197], v[136:137]
	v_cvt_pk_bf16_f32 v144, v144, v145
	v_cvt_pk_bf16_f32 v145, v146, v147
	v_pk_mul_f32 v[134:135], v[134:135], v[142:143]
	v_cvt_pk_bf16_f32 v146, v150, v151
	v_cvt_pk_bf16_f32 v147, v148, v149
	v_lshl_add_u64 v[148:149], v[176:177], 1, s[34:35]
	v_pk_mul_f32 v[132:133], v[132:133], v[140:141]
	global_store_dwordx4 v[148:149], v[144:147], off
	v_pk_mul_f32 v[128:129], v[128:129], v[136:137]
	v_pk_mul_f32 v[130:131], v[130:131], v[138:139]
	v_mov_b32_e32 v145, v132
	v_mov_b32_e32 v132, v141
	v_mov_b32_e32 v141, v134
	v_mov_b32_e32 v134, v143
	v_mov_b32_e32 v144, v140
	v_pk_mul_f32 v[132:133], v[132:133], v[132:133]
	v_mov_b32_e32 v140, v142
	v_pk_mul_f32 v[134:135], v[134:135], v[134:135]
	v_pk_fma_f32 v[132:133], v[144:145], v[144:145], v[132:133]
	v_pk_fma_f32 v[134:135], v[140:141], v[140:141], v[134:135]
	s_nop 0
	v_pk_add_f32 v[132:133], v[132:133], v[134:135]
	v_mov_b32_e32 v135, v128
	v_mov_b32_e32 v128, v137
	v_mov_b32_e32 v134, v136
	v_pk_mul_f32 v[128:129], v[128:129], v[128:129]
	s_nop 0
	v_pk_fma_f32 v[128:129], v[134:135], v[134:135], v[128:129]
	v_mov_b32_e32 v135, v130
	v_mov_b32_e32 v130, v139
	v_mov_b32_e32 v134, v138
	v_pk_mul_f32 v[130:131], v[130:131], v[130:131]
	s_nop 0
	v_pk_fma_f32 v[130:131], v[134:135], v[134:135], v[130:131]
	s_nop 0
	v_pk_add_f32 v[128:129], v[128:129], v[130:131]
	s_nop 0
	v_pk_add_f32 v[186:187], v[132:133], v[128:129]
	s_branch .LBB0_405

;     static __device__ __forceinline__ void run(const f32x4 (&acc)[2][2][4][2], const Unit& u, int wr, int wc, int fr, int fq, const float* xin, float* xout, const float* gate, float gs, const float* lazy_ssq, const float* lazy_g, ...
;     ...
;                 gv[n] = *(const f32x4*)(gate + (b * 9216u + col + 4 * n)) * gs;
;                 lg[n] = (f32x4){1.f, 1.f, 1.f, 1.f}; if (LAZY) lg[n] = *(const f32x4*)(lazy_g + col + 4 * n);
;                 wv[n] = (f32x4){0.f, 0.f, 0.f, 0.f}; w2[n] = (f32x4){1.f, 1.f, 1.f, 1.f};
;                 if (aout) { wv[n] = *(const f32x4*)(wg + col + 4 * n) * (*(const f32x4*)(wsc + (b * 9216u + col + 4 * n)) + 1.0f); if (WG2) { w2[n] = *(const f32x4*)(wg2 + col + 4 * n); wv[n] = wv[n] * w2[n]; } }
;             }
;             f32x4 xq[2][2][2];
;     ...
;             constexpr bool DEEP = !LAZY && !WG2;
;             if (DEEP) RES_LD(0, 0);
; #pragma unroll
;             for (int pp = 0; pp < 4; ++pp) {
;                 if (DEEP) { if (pp < 3) RES_LD((pp + 1) & 1, pp + 1); } else RES_LD(pp & 1, pp);
; #pragma unroll
;                 for (int j = 0; j < 2; ++j) { const int i_ = 2 * pp + j, ai = i_ >> 2, m = i_ & 3; const unsigned off = (row0 + ai * HALF + m * 16) * 1024u + col;
;                     const f32x4 xi0 = xq[pp & 1][j][0], xi1 = xq[pp & 1][j][1];
;                     f32x4 xo0 = gv[0] * acc[ai][bj][m][0], xo1 = gv[1] * acc[ai][bj][m][1];
;                     if (LAZY) { xo0 = xo0 + xi0 * lg[0] * rl[ai][m]; xo1 = xo1 + xi1 * lg[1] * rl[ai][m]; } else { xo0 = xo0 + xi0; xo1 = xo1 + xi1; }
;                     *(f32x4*)(xout + off) = xo0; *(f32x4*)(xout + off + 4) = xo1;
;                     if (aout) { const f32x4 a0 = xo0 * wv[0], a1 = xo1 * wv[1]; u32x4 w; w.x = cvt_pk_bf16(a0[0], a0[1]); w.y = cvt_pk_bf16(a0[2], a0[3]); w.z = cvt_pk_bf16(a1[0], a1[1]); w.w = cvt_pk_bf16(a1[2], a1[3]);
;                         *(u32x4*)(aout + off) = w;
;                         sq[ai][m] += ((xo0[0] * xo0[0] + xo0[1] * xo0[1]) + (xo0[2] * xo0[2] + xo0[3] * xo0[3])) + ((xo1[0] * xo1[0] + xo1[1] * xo1[1]) + (xo1[2] * xo1[2] + xo1[3] * xo1[3]));
;                         if (WG2) { const f32x4 b0 = xo0 * w2[0], b1 = xo1 * w2[1]; sqb[ai][m] += ((b0[0] * b0[0] + b0[1] * b0[1]) + (b0[2] * b0[2] + b0[3] * b0[3])) + ((b1[0] * b1[0] + b1[1] * b1[1]) + (b1[2] * b1[2] + b1[3] * b1[3])); } } }
.LBB0_409:
	v_add_u32_e32 v176, v208, v153
	v_lshlrev_b64 v[206:207], 2, v[176:177]
	v_lshl_add_u64 v[144:145], s[38:39], 0, v[206:207]
	v_mov_b32_e32 v205, v177
	v_add_u32_e32 v204, 0x4000, v176
	global_load_dwordx4 v[210:213], v[144:145], off
	global_load_dwordx4 v[232:235], v[144:145], off offset:16
	v_lshl_add_u64 v[148:149], v[204:205], 2, s[38:39]
	global_load_dwordx4 v[144:147], v[148:149], off offset:16
	s_nop 0
	global_load_dwordx4 v[148:151], v[148:149], off
	s_mov_b32 s41, s40
	s_mov_b32 s42, s40
	s_mov_b32 s43, s40
	s_waitcnt vmcnt(0)
	v_pk_mul_f32 v[190:191], s[42:43], v[142:143]
	v_pk_mul_f32 v[188:189], s[40:41], v[140:141]
	v_pk_mul_f32 v[200:201], s[42:43], v[138:139]
	v_pk_mul_f32 v[202:203], s[40:41], v[136:137]
	s_and_b64 vcc, exec, s[8:9]
	v_lshl_add_u64 v[206:207], s[36:37], 0, v[206:207]
	s_waitcnt vmcnt(0)
	v_pk_fma_f32 v[142:143], v[118:119], v[200:201], v[212:213]
	v_pk_fma_f32 v[140:141], v[116:117], v[202:203], v[210:211]
	s_waitcnt vmcnt(0)
	v_pk_fma_f32 v[138:139], v[114:115], v[190:191], v[234:235]
	v_pk_fma_f32 v[136:137], v[112:113], v[188:189], v[232:233]
	global_store_dwordx4 v[206:207], v[140:143], off
	global_store_dwordx4 v[206:207], v[136:139], off offset:16
	s_cbranch_vccnz .LBB0_411
	v_pk_mul_f32 v[206:207], v[196:197], v[142:143]
	v_pk_mul_f32 v[210:211], v[194:195], v[140:141]
	v_pk_mul_f32 v[212:213], v[192:193], v[136:137]
	v_cvt_pk_bf16_f32 v210, v210, v211
	v_cvt_pk_bf16_f32 v211, v206, v207
	v_lshl_add_u64 v[206:207], v[176:177], 1, s[34:35]
	v_pk_mul_f32 v[214:215], v[198:199], v[138:139]
	v_cvt_pk_bf16_f32 v212, v212, v213
	v_mov_b32_e32 v232, v140
	v_cvt_pk_bf16_f32 v213, v214, v215
	global_store_dwordx4 v[206:207], v[210:213], off
	v_pk_mul_f32 v[206:207], v[134:135], v[142:143]
	v_pk_mul_f32 v[214:215], v[128:129], v[136:137]
	v_pk_mul_f32 v[210:211], v[132:133], v[140:141]
	v_pk_mul_f32 v[212:213], v[130:131], v[138:139]
	v_mov_b32_e32 v233, v210
	v_mov_b32_e32 v210, v141
	v_pk_mul_f32 v[140:141], v[210:211], v[210:211]
	v_mov_b32_e32 v211, v206
	v_mov_b32_e32 v206, v143
	v_mov_b32_e32 v210, v142
	v_pk_mul_f32 v[142:143], v[206:207], v[206:207]
	v_pk_fma_f32 v[140:141], v[232:233], v[232:233], v[140:141]
	v_pk_fma_f32 v[142:143], v[210:211], v[210:211], v[142:143]
	s_nop 0
	v_pk_add_f32 v[140:141], v[140:141], v[142:143]
	v_mov_b32_e32 v143, v214
	v_mov_b32_e32 v214, v137
	v_mov_b32_e32 v142, v136
	v_pk_mul_f32 v[136:137], v[214:215], v[214:215]
	s_nop 0
	v_pk_fma_f32 v[136:137], v[142:143], v[142:143], v[136:137]
	v_mov_b32_e32 v143, v212
	v_mov_b32_e32 v212, v139
	v_mov_b32_e32 v142, v138
	v_pk_mul_f32 v[138:139], v[212:213], v[212:213]
	s_nop 0
	v_pk_fma_f32 v[138:139], v[142:143], v[142:143], v[138:139]
	s_nop 0
	v_pk_add_f32 v[136:137], v[136:137], v[138:139]
	s_nop 0
	v_pk_add_f32 v[136:137], v[140:141], v[136:137]
	s_nop 0
	v_pk_add_f32 v[154:155], v[154:155], v[136:137]
.LBB0_411:
	s_waitcnt vmcnt(0)
	v_pk_fma_f32 v[142:143], v[102:103], v[200:201], v[150:151]
	v_pk_fma_f32 v[140:141], v[100:101], v[202:203], v[148:149]
	v_pk_fma_f32 v[138:139], v[98:99], v[190:191], v[146:147]
	v_pk_fma_f32 v[136:137], v[96:97], v[188:189], v[144:145]
	v_lshl_add_u64 v[144:145], v[204:205], 2, s[36:37]
	s_and_b64 vcc, exec, s[8:9]
	global_store_dwordx4 v[144:145], v[140:143], off
	global_store_dwordx4 v[144:145], v[136:139], off offset:16
	s_cbranch_vccnz .LBB0_413
	v_pk_mul_f32 v[146:147], v[196:197], v[142:143]
	v_pk_mul_f32 v[144:145], v[194:195], v[140:141]
	v_pk_mul_f32 v[148:149], v[198:199], v[138:139]
	v_pk_mul_f32 v[150:151], v[192:193], v[136:137]
	v_cvt_pk_bf16_f32 v144, v144, v145
	v_cvt_pk_bf16_f32 v145, v146, v147
	s_nop 0
	v_cvt_pk_bf16_f32 v146, v150, v151
	v_cvt_pk_bf16_f32 v147, v148, v149
	v_lshl_add_u64 v[148:149], v[204:205], 1, s[34:35]
	global_store_dwordx4 v[148:149], v[144:147], off
	v_mov_b32_e32 v204, v140
	v_pk_mul_f32 v[150:151], v[128:129], v[136:137]
	v_pk_mul_f32 v[146:147], v[132:133], v[140:141]
	v_pk_mul_f32 v[144:145], v[134:135], v[142:143]
	v_mov_b32_e32 v205, v146
	v_mov_b32_e32 v146, v141
	v_pk_mul_f32 v[140:141], v[146:147], v[146:147]
	v_mov_b32_e32 v147, v144
	v_mov_b32_e32 v144, v143
	v_mov_b32_e32 v146, v142
	v_pk_mul_f32 v[142:143], v[144:145], v[144:145]
	v_pk_fma_f32 v[140:141], v[204:205], v[204:205], v[140:141]
	v_pk_fma_f32 v[142:143], v[146:147], v[146:147], v[142:143]
	v_pk_mul_f32 v[148:149], v[130:131], v[138:139]
	v_pk_add_f32 v[140:141], v[140:141], v[142:143]
	v_mov_b32_e32 v143, v150
	v_mov_b32_e32 v150, v137
	v_mov_b32_e32 v142, v136
	v_pk_mul_f32 v[136:137], v[150:151], v[150:151]
	s_nop 0
	v_pk_fma_f32 v[136:137], v[142:143], v[142:143], v[136:137]
	v_mov_b32_e32 v143, v148
	v_mov_b32_e32 v148, v139
	v_mov_b32_e32 v142, v138
	v_pk_mul_f32 v[138:139], v[148:149], v[148:149]
	s_nop 0
	v_pk_fma_f32 v[138:139], v[142:143], v[142:143], v[138:139]
	s_nop 0
	v_pk_add_f32 v[136:137], v[136:137], v[138:139]
	s_nop 0
	v_pk_add_f32 v[136:137], v[140:141], v[136:137]
	s_nop 0
	v_pk_add_f32 v[156:157], v[156:157], v[136:137]
; __device__ __forceinline__ unsigned cvt_pk_bf16(float lo, float hi) { unsigned r; asm volatile("v_cvt_pk_bf16_f32 %0, %1, %2" : "=v"(r) : "v"(lo), "v"(hi)); return r; }
; #define RES_LD(buf, pp) do { _Pragma("unroll") for (int j = 0; j < 2; ++j) { const int i_ = 2 * (pp) + j; const unsigned off_ = (row0 + (i_ >> 2) * HALF + (i_ & 3) * 16) * 1024u + col; \
;                 xq[buf][j][0] = *(const f32x4*)(xin + off_); xq[buf][j][1] = *(const f32x4*)(xin + off_ + 4); } } while (0)
;     static __device__ __forceinline__ void run(const f32x4 (&acc)[2][2][4][2], const Unit& u, int wr, int wc, int fr, int fq, const float* xin, float* xout, const float* gate, float gs, const float* lazy_ssq, const float* lazy_g, ...
;     ...
;             constexpr bool DEEP = !LAZY && !WG2;
;             if (DEEP) RES_LD(0, 0);
; #pragma unroll
;             for (int pp = 0; pp < 4; ++pp) {
;                 if (DEEP) { if (pp < 3) RES_LD((pp + 1) & 1, pp + 1); } else RES_LD(pp & 1, pp);
; #pragma unroll
;                 for (int j = 0; j < 2; ++j) { const int i_ = 2 * pp + j, ai = i_ >> 2, m = i_ & 3; const unsigned off = (row0 + ai * HALF + m * 16) * 1024u + col;
;                     const f32x4 xi0 = xq[pp & 1][j][0], xi1 = xq[pp & 1][j][1];
;                     f32x4 xo0 = gv[0] * acc[ai][bj][m][0], xo1 = gv[1] * acc[ai][bj][m][1];
;                     if (LAZY) { xo0 = xo0 + xi0 * lg[0] * rl[ai][m]; xo1 = xo1 + xi1 * lg[1] * rl[ai][m]; } else { xo0 = xo0 + xi0; xo1 = xo1 + xi1; }
;                     *(f32x4*)(xout + off) = xo0; *(f32x4*)(xout + off + 4) = xo1;
;                     if (aout) { const f32x4 a0 = xo0 * wv[0], a1 = xo1 * wv[1]; u32x4 w; w.x = cvt_pk_bf16(a0[0], a0[1]); w.y = cvt_pk_bf16(a0[2], a0[3]); w.z = cvt_pk_bf16(a1[0], a1[1]); w.w = cvt_pk_bf16(a1[2], a1[3]);
;                         *(u32x4*)(aout + off) = w;
;                         sq[ai][m] += ((xo0[0] * xo0[0] + xo0[1] * xo0[1]) + (xo0[2] * xo0[2] + xo0[3] * xo0[3])) + ((xo1[0] * xo1[0] + xo1[1] * xo1[1]) + (xo1[2] * xo1[2] + xo1[3] * xo1[3]));
;                         if (WG2) { const f32x4 b0 = xo0 * w2[0], b1 = xo1 * w2[1]; sqb[ai][m] += ((b0[0] * b0[0] + b0[1] * b0[1]) + (b0[2] * b0[2] + b0[3] * b0[3])) + ((b1[0] * b1[0] + b1[1] * b1[1]) + (b1[2] * b1[2] + b1[3] * b1[3])); } } }
.LBB0_413:
	v_add_u32_e32 v206, 0x8000, v176
	v_mov_b32_e32 v207, v177
	v_lshlrev_b64 v[148:149], 2, v[206:207]
	v_lshl_add_u64 v[136:137], s[38:39], 0, v[148:149]
	v_add_u32_e32 v204, 0xc000, v176
	v_mov_b32_e32 v205, v177
	global_load_dwordx4 v[144:147], v[136:137], off
	global_load_dwordx4 v[210:213], v[136:137], off offset:16
	v_lshl_add_u64 v[140:141], v[204:205], 2, s[38:39]
	global_load_dwordx4 v[136:139], v[140:141], off offset:16
	s_nop 0
	global_load_dwordx4 v[140:143], v[140:141], off
	s_and_b64 vcc, exec, s[8:9]
	v_lshl_add_u64 v[214:215], s[36:37], 0, v[148:149]
	s_waitcnt vmcnt(0)
	v_pk_fma_f32 v[150:151], v[86:87], v[200:201], v[146:147]
	v_pk_fma_f32 v[148:149], v[84:85], v[202:203], v[144:145]
	s_waitcnt vmcnt(0)
	v_pk_fma_f32 v[146:147], v[82:83], v[190:191], v[212:213]
	v_pk_fma_f32 v[144:145], v[80:81], v[188:189], v[210:211]
	global_store_dwordx4 v[214:215], v[148:151], off
	global_store_dwordx4 v[214:215], v[144:147], off offset:16
	s_cbranch_vccnz .LBB0_415
	v_pk_mul_f32 v[210:211], v[194:195], v[148:149]
	v_pk_mul_f32 v[212:213], v[196:197], v[150:151]
	v_cvt_pk_bf16_f32 v210, v210, v211
	v_lshl_add_u64 v[206:207], v[206:207], 1, s[34:35]
	v_cvt_pk_bf16_f32 v211, v212, v213
	v_pk_mul_f32 v[214:215], v[198:199], v[146:147]
	v_pk_mul_f32 v[232:233], v[192:193], v[144:145]
	s_nop 0
	v_cvt_pk_bf16_f32 v212, v232, v233
	v_cvt_pk_bf16_f32 v213, v214, v215
	global_store_dwordx4 v[206:207], v[210:213], off
	v_pk_mul_f32 v[206:207], v[134:135], v[150:151]
	v_mov_b32_e32 v232, v148
	v_pk_mul_f32 v[210:211], v[132:133], v[148:149]
	v_pk_mul_f32 v[214:215], v[128:129], v[144:145]
	v_mov_b32_e32 v233, v210
	v_mov_b32_e32 v210, v149
	v_pk_mul_f32 v[148:149], v[210:211], v[210:211]
	v_mov_b32_e32 v211, v206
	v_mov_b32_e32 v206, v151
	v_mov_b32_e32 v210, v150
	v_pk_mul_f32 v[150:151], v[206:207], v[206:207]
	v_pk_fma_f32 v[148:149], v[232:233], v[232:233], v[148:149]
	v_pk_fma_f32 v[150:151], v[210:211], v[210:211], v[150:151]
	v_pk_mul_f32 v[212:213], v[130:131], v[146:147]
	v_pk_add_f32 v[148:149], v[148:149], v[150:151]
	v_mov_b32_e32 v151, v214
	v_mov_b32_e32 v214, v145
	v_mov_b32_e32 v150, v144
	v_pk_mul_f32 v[144:145], v[214:215], v[214:215]
	s_nop 0
	v_pk_fma_f32 v[144:145], v[150:151], v[150:151], v[144:145]
	v_mov_b32_e32 v151, v212
	v_mov_b32_e32 v212, v147
	v_mov_b32_e32 v150, v146
	v_pk_mul_f32 v[146:147], v[212:213], v[212:213]
	s_nop 0
	v_pk_fma_f32 v[146:147], v[150:151], v[150:151], v[146:147]
	s_nop 0
	v_pk_add_f32 v[144:145], v[144:145], v[146:147]
	s_nop 0
	v_pk_add_f32 v[144:145], v[148:149], v[144:145]
	s_nop 0
	v_pk_add_f32 v[158:159], v[158:159], v[144:145]
.LBB0_415:
	s_waitcnt vmcnt(0)
	v_pk_fma_f32 v[142:143], v[70:71], v[200:201], v[142:143]
	v_pk_fma_f32 v[140:141], v[68:69], v[202:203], v[140:141]
	v_pk_fma_f32 v[138:139], v[66:67], v[190:191], v[138:139]
	v_pk_fma_f32 v[136:137], v[64:65], v[188:189], v[136:137]
	v_lshl_add_u64 v[144:145], v[204:205], 2, s[36:37]
	s_and_b64 vcc, exec, s[8:9]
	global_store_dwordx4 v[144:145], v[140:143], off
	global_store_dwordx4 v[144:145], v[136:139], off offset:16
	s_cbranch_vccnz .LBB0_417
	v_pk_mul_f32 v[146:147], v[196:197], v[142:143]
	v_pk_mul_f32 v[144:145], v[194:195], v[140:141]
	v_pk_mul_f32 v[148:149], v[198:199], v[138:139]
	v_pk_mul_f32 v[150:151], v[192:193], v[136:137]
	v_cvt_pk_bf16_f32 v144, v144, v145
	v_cvt_pk_bf16_f32 v145, v146, v147
	s_nop 0
	v_cvt_pk_bf16_f32 v146, v150, v151
	v_cvt_pk_bf16_f32 v147, v148, v149
	v_lshl_add_u64 v[148:149], v[204:205], 1, s[34:35]
	global_store_dwordx4 v[148:149], v[144:147], off
	v_mov_b32_e32 v204, v140
	v_pk_mul_f32 v[150:151], v[128:129], v[136:137]
	v_pk_mul_f32 v[146:147], v[132:133], v[140:141]
	v_pk_mul_f32 v[144:145], v[134:135], v[142:143]
	v_mov_b32_e32 v205, v146
	v_mov_b32_e32 v146, v141
	v_pk_mul_f32 v[140:141], v[146:147], v[146:147]
	v_mov_b32_e32 v147, v144
	v_mov_b32_e32 v144, v143
	v_mov_b32_e32 v146, v142
	v_pk_mul_f32 v[142:143], v[144:145], v[144:145]
	v_pk_fma_f32 v[140:141], v[204:205], v[204:205], v[140:141]
	v_pk_fma_f32 v[142:143], v[146:147], v[146:147], v[142:143]
	v_pk_mul_f32 v[148:149], v[130:131], v[138:139]
	v_pk_add_f32 v[140:141], v[140:141], v[142:143]
	v_mov_b32_e32 v143, v150
	v_mov_b32_e32 v150, v137
	v_mov_b32_e32 v142, v136
	v_pk_mul_f32 v[136:137], v[150:151], v[150:151]
	s_nop 0
	v_pk_fma_f32 v[136:137], v[142:143], v[142:143], v[136:137]
	v_mov_b32_e32 v143, v148
	v_mov_b32_e32 v148, v139
	v_mov_b32_e32 v142, v138
	v_pk_mul_f32 v[138:139], v[148:149], v[148:149]
	s_nop 0
	v_pk_fma_f32 v[138:139], v[142:143], v[142:143], v[138:139]
	s_nop 0
	v_pk_add_f32 v[136:137], v[136:137], v[138:139]
	s_nop 0
	v_pk_add_f32 v[136:137], v[140:141], v[136:137]
	s_nop 0
	v_pk_add_f32 v[174:175], v[174:175], v[136:137]
; __device__ __forceinline__ unsigned cvt_pk_bf16(float lo, float hi) { unsigned r; asm volatile("v_cvt_pk_bf16_f32 %0, %1, %2" : "=v"(r) : "v"(lo), "v"(hi)); return r; }
; #define RES_LD(buf, pp) do { _Pragma("unroll") for (int j = 0; j < 2; ++j) { const int i_ = 2 * (pp) + j; const unsigned off_ = (row0 + (i_ >> 2) * HALF + (i_ & 3) * 16) * 1024u + col; \
;                 xq[buf][j][0] = *(const f32x4*)(xin + off_); xq[buf][j][1] = *(const f32x4*)(xin + off_ + 4); } } while (0)
;     static __device__ __forceinline__ void run(const f32x4 (&acc)[2][2][4][2], const Unit& u, int wr, int wc, int fr, int fq, const float* xin, float* xout, const float* gate, float gs, const float* lazy_ssq, const float* lazy_g, ...
;     ...
;             constexpr bool DEEP = !LAZY && !WG2;
;             if (DEEP) RES_LD(0, 0);
; #pragma unroll
;             for (int pp = 0; pp < 4; ++pp) {
;                 if (DEEP) { if (pp < 3) RES_LD((pp + 1) & 1, pp + 1); } else RES_LD(pp & 1, pp);
; #pragma unroll
;                 for (int j = 0; j < 2; ++j) { const int i_ = 2 * pp + j, ai = i_ >> 2, m = i_ & 3; const unsigned off = (row0 + ai * HALF + m * 16) * 1024u + col;
;                     const f32x4 xi0 = xq[pp & 1][j][0], xi1 = xq[pp & 1][j][1];
;                     f32x4 xo0 = gv[0] * acc[ai][bj][m][0], xo1 = gv[1] * acc[ai][bj][m][1];
;                     if (LAZY) { xo0 = xo0 + xi0 * lg[0] * rl[ai][m]; xo1 = xo1 + xi1 * lg[1] * rl[ai][m]; } else { xo0 = xo0 + xi0; xo1 = xo1 + xi1; }
;                     *(f32x4*)(xout + off) = xo0; *(f32x4*)(xout + off + 4) = xo1;
;                     if (aout) { const f32x4 a0 = xo0 * wv[0], a1 = xo1 * wv[1]; u32x4 w; w.x = cvt_pk_bf16(a0[0], a0[1]); w.y = cvt_pk_bf16(a0[2], a0[3]); w.z = cvt_pk_bf16(a1[0], a1[1]); w.w = cvt_pk_bf16(a1[2], a1[3]);
;                         *(u32x4*)(aout + off) = w;
;                         sq[ai][m] += ((xo0[0] * xo0[0] + xo0[1] * xo0[1]) + (xo0[2] * xo0[2] + xo0[3] * xo0[3])) + ((xo1[0] * xo1[0] + xo1[1] * xo1[1]) + (xo1[2] * xo1[2] + xo1[3] * xo1[3]));
;                         if (WG2) { const f32x4 b0 = xo0 * w2[0], b1 = xo1 * w2[1]; sqb[ai][m] += ((b0[0] * b0[0] + b0[1] * b0[1]) + (b0[2] * b0[2] + b0[3] * b0[3])) + ((b1[0] * b1[0] + b1[1] * b1[1]) + (b1[2] * b1[2] + b1[3] * b1[3])); } } }
.LBB0_417:
	v_add_u32_e32 v204, v173, v208
	v_mov_b32_e32 v205, v177
	v_lshl_add_u64 v[136:137], v[204:205], 2, s[38:39]
	global_load_dwordx4 v[144:147], v[136:137], off offset:16
	global_load_dwordx4 v[148:151], v[136:137], off
	v_add_u32_e32 v136, 0x4000, v204
	v_mov_b32_e32 v137, v177
	v_lshl_add_u64 v[140:141], v[136:137], 2, s[38:39]
	global_load_dwordx4 v[136:139], v[140:141], off offset:16
	s_nop 0
	global_load_dwordx4 v[140:143], v[140:141], off
	v_add_u32_e32 v206, 0x20000, v176
	v_mov_b32_e32 v207, v177
	v_lshl_add_u64 v[208:209], v[206:207], 2, s[36:37]
	s_and_b64 vcc, exec, s[8:9]
	s_waitcnt vmcnt(0)
	v_pk_fma_f32 v[146:147], v[50:51], v[190:191], v[146:147]
	s_waitcnt vmcnt(0)
	v_pk_fma_f32 v[150:151], v[54:55], v[200:201], v[150:151]
	v_pk_fma_f32 v[148:149], v[52:53], v[202:203], v[148:149]
	v_pk_fma_f32 v[144:145], v[48:49], v[188:189], v[144:145]
	global_store_dwordx4 v[208:209], v[148:151], off
	global_store_dwordx4 v[208:209], v[144:147], off offset:16
	s_cbranch_vccnz .LBB0_419
	v_pk_mul_f32 v[208:209], v[194:195], v[148:149]
	v_pk_mul_f32 v[210:211], v[196:197], v[150:151]
	v_cvt_pk_bf16_f32 v208, v208, v209
	v_lshl_add_u64 v[206:207], v[206:207], 1, s[34:35]
	v_cvt_pk_bf16_f32 v209, v210, v211
	v_pk_mul_f32 v[212:213], v[198:199], v[146:147]
	v_pk_mul_f32 v[214:215], v[192:193], v[144:145]
	s_nop 0
	v_cvt_pk_bf16_f32 v210, v214, v215
	v_cvt_pk_bf16_f32 v211, v212, v213
	global_store_dwordx4 v[206:207], v[208:211], off
	v_pk_mul_f32 v[206:207], v[134:135], v[150:151]
	v_mov_b32_e32 v214, v148
	v_pk_mul_f32 v[208:209], v[132:133], v[148:149]
	v_pk_mul_f32 v[212:213], v[128:129], v[144:145]
	v_mov_b32_e32 v215, v208
	v_mov_b32_e32 v208, v149
	v_pk_mul_f32 v[148:149], v[208:209], v[208:209]
	v_mov_b32_e32 v209, v206
	v_mov_b32_e32 v206, v151
	v_mov_b32_e32 v208, v150
	v_pk_mul_f32 v[150:151], v[206:207], v[206:207]
	v_pk_fma_f32 v[148:149], v[214:215], v[214:215], v[148:149]
	v_pk_fma_f32 v[150:151], v[208:209], v[208:209], v[150:151]
	v_pk_mul_f32 v[210:211], v[130:131], v[146:147]
	v_pk_add_f32 v[148:149], v[148:149], v[150:151]
	v_mov_b32_e32 v151, v212
	v_mov_b32_e32 v212, v145
	v_mov_b32_e32 v150, v144
	v_pk_mul_f32 v[144:145], v[212:213], v[212:213]
	s_nop 0
	v_pk_fma_f32 v[144:145], v[150:151], v[150:151], v[144:145]
	v_mov_b32_e32 v151, v210
	v_mov_b32_e32 v210, v147
	v_mov_b32_e32 v150, v146
	v_pk_mul_f32 v[146:147], v[210:211], v[210:211]
	s_nop 0
	v_pk_fma_f32 v[146:147], v[150:151], v[150:151], v[146:147]
	s_nop 0
	v_pk_add_f32 v[144:145], v[144:145], v[146:147]
	s_nop 0
	v_pk_add_f32 v[144:145], v[148:149], v[144:145]
	s_nop 0
	v_pk_add_f32 v[180:181], v[180:181], v[144:145]
.LBB0_419:
	s_nop 0
	v_add_u32_e32 v144, 0x24000, v176
	v_mov_b32_e32 v145, v177
	s_waitcnt vmcnt(0)
	v_pk_fma_f32 v[142:143], v[38:39], v[200:201], v[142:143]
	v_pk_fma_f32 v[140:141], v[36:37], v[202:203], v[140:141]
	v_pk_fma_f32 v[138:139], v[34:35], v[190:191], v[138:139]
	v_pk_fma_f32 v[136:137], v[32:33], v[188:189], v[136:137]
	v_lshl_add_u64 v[146:147], v[144:145], 2, s[36:37]
	s_and_b64 vcc, exec, s[8:9]
	global_store_dwordx4 v[146:147], v[140:143], off
	global_store_dwordx4 v[146:147], v[136:139], off offset:16
	s_cbranch_vccnz .LBB0_421
	v_pk_mul_f32 v[146:147], v[194:195], v[140:141]
	v_pk_mul_f32 v[148:149], v[196:197], v[142:143]
	v_cvt_pk_bf16_f32 v146, v146, v147
	v_lshl_add_u64 v[144:145], v[144:145], 1, s[34:35]
	v_cvt_pk_bf16_f32 v147, v148, v149
	v_pk_mul_f32 v[150:151], v[198:199], v[138:139]
	v_pk_mul_f32 v[206:207], v[192:193], v[136:137]
	s_nop 0
	v_cvt_pk_bf16_f32 v148, v206, v207
	v_cvt_pk_bf16_f32 v149, v150, v151
	global_store_dwordx4 v[144:145], v[146:149], off
	v_pk_mul_f32 v[144:145], v[134:135], v[142:143]
	v_mov_b32_e32 v206, v140
	v_pk_mul_f32 v[146:147], v[132:133], v[140:141]
	v_pk_mul_f32 v[150:151], v[128:129], v[136:137]
	v_mov_b32_e32 v207, v146
	v_mov_b32_e32 v146, v141
	v_pk_mul_f32 v[140:141], v[146:147], v[146:147]
	v_mov_b32_e32 v147, v144
	v_mov_b32_e32 v144, v143
	v_mov_b32_e32 v146, v142
	v_pk_mul_f32 v[142:143], v[144:145], v[144:145]
	v_pk_fma_f32 v[140:141], v[206:207], v[206:207], v[140:141]
	v_pk_fma_f32 v[142:143], v[146:147], v[146:147], v[142:143]
	v_pk_mul_f32 v[148:149], v[130:131], v[138:139]
	v_pk_add_f32 v[140:141], v[140:141], v[142:143]
	v_mov_b32_e32 v143, v150
	v_mov_b32_e32 v150, v137
	v_mov_b32_e32 v142, v136
	v_pk_mul_f32 v[136:137], v[150:151], v[150:151]
	s_nop 0
	v_pk_fma_f32 v[136:137], v[142:143], v[142:143], v[136:137]
	v_mov_b32_e32 v143, v148
	v_mov_b32_e32 v148, v139
	v_mov_b32_e32 v142, v138
	v_pk_mul_f32 v[138:139], v[148:149], v[148:149]
	s_nop 0
	v_pk_fma_f32 v[138:139], v[142:143], v[142:143], v[138:139]
	s_nop 0
	v_pk_add_f32 v[136:137], v[136:137], v[138:139]
	s_nop 0
	v_pk_add_f32 v[136:137], v[140:141], v[136:137]
	s_nop 0
	v_pk_add_f32 v[182:183], v[182:183], v[136:137]
; __device__ __forceinline__ unsigned cvt_pk_bf16(float lo, float hi) { unsigned r; asm volatile("v_cvt_pk_bf16_f32 %0, %1, %2" : "=v"(r) : "v"(lo), "v"(hi)); return r; }
; #define RES_LD(buf, pp) do { _Pragma("unroll") for (int j = 0; j < 2; ++j) { const int i_ = 2 * (pp) + j; const unsigned off_ = (row0 + (i_ >> 2) * HALF + (i_ & 3) * 16) * 1024u + col; \
;                 xq[buf][j][0] = *(const f32x4*)(xin + off_); xq[buf][j][1] = *(const f32x4*)(xin + off_ + 4); } } while (0)
;     static __device__ __forceinline__ void run(const f32x4 (&acc)[2][2][4][2], const Unit& u, int wr, int wc, int fr, int fq, const float* xin, float* xout, const float* gate, float gs, const float* lazy_ssq, const float* lazy_g, ...
;     ...
;             constexpr bool DEEP = !LAZY && !WG2;
;             if (DEEP) RES_LD(0, 0);
; #pragma unroll
;             for (int pp = 0; pp < 4; ++pp) {
;                 if (DEEP) { if (pp < 3) RES_LD((pp + 1) & 1, pp + 1); } else RES_LD(pp & 1, pp);
; #pragma unroll
;                 for (int j = 0; j < 2; ++j) { const int i_ = 2 * pp + j, ai = i_ >> 2, m = i_ & 3; const unsigned off = (row0 + ai * HALF + m * 16) * 1024u + col;
;                     const f32x4 xi0 = xq[pp & 1][j][0], xi1 = xq[pp & 1][j][1];
;                     f32x4 xo0 = gv[0] * acc[ai][bj][m][0], xo1 = gv[1] * acc[ai][bj][m][1];
;                     if (LAZY) { xo0 = xo0 + xi0 * lg[0] * rl[ai][m]; xo1 = xo1 + xi1 * lg[1] * rl[ai][m]; } else { xo0 = xo0 + xi0; xo1 = xo1 + xi1; }
;                     *(f32x4*)(xout + off) = xo0; *(f32x4*)(xout + off + 4) = xo1;
;                     if (aout) { const f32x4 a0 = xo0 * wv[0], a1 = xo1 * wv[1]; u32x4 w; w.x = cvt_pk_bf16(a0[0], a0[1]); w.y = cvt_pk_bf16(a0[2], a0[3]); w.z = cvt_pk_bf16(a1[0], a1[1]); w.w = cvt_pk_bf16(a1[2], a1[3]);
;                         *(u32x4*)(aout + off) = w;
;                         sq[ai][m] += ((xo0[0] * xo0[0] + xo0[1] * xo0[1]) + (xo0[2] * xo0[2] + xo0[3] * xo0[3])) + ((xo1[0] * xo1[0] + xo1[1] * xo1[1]) + (xo1[2] * xo1[2] + xo1[3] * xo1[3]));
;                         if (WG2) { const f32x4 b0 = xo0 * w2[0], b1 = xo1 * w2[1]; sqb[ai][m] += ((b0[0] * b0[0] + b0[1] * b0[1]) + (b0[2] * b0[2] + b0[3] * b0[3])) + ((b1[0] * b1[0] + b1[1] * b1[1]) + (b1[2] * b1[2] + b1[3] * b1[3])); } } }
.LBB0_421:
	s_nop 0
	v_add_u32_e32 v136, 0x8000, v204
	v_mov_b32_e32 v137, v177
	v_lshl_add_u64 v[136:137], v[136:137], 2, s[38:39]
	global_load_dwordx4 v[144:147], v[136:137], off offset:16
	global_load_dwordx4 v[148:151], v[136:137], off
	v_add_u32_e32 v136, 0xc000, v204
	v_mov_b32_e32 v137, v177
	v_lshl_add_u64 v[140:141], v[136:137], 2, s[38:39]
	global_load_dwordx4 v[136:139], v[140:141], off offset:16
	s_nop 0
	global_load_dwordx4 v[140:143], v[140:141], off
	v_add_u32_e32 v204, 0x28000, v176
	v_mov_b32_e32 v205, v177
	v_lshl_add_u64 v[206:207], v[204:205], 2, s[36:37]
	s_and_b64 vcc, exec, s[8:9]
	s_waitcnt vmcnt(0)
	v_pk_fma_f32 v[146:147], v[18:19], v[190:191], v[146:147]
	s_waitcnt vmcnt(0)
	v_pk_fma_f32 v[150:151], v[22:23], v[200:201], v[150:151]
	v_pk_fma_f32 v[148:149], v[20:21], v[202:203], v[148:149]
	v_pk_fma_f32 v[144:145], v[16:17], v[188:189], v[144:145]
	global_store_dwordx4 v[206:207], v[148:151], off
	global_store_dwordx4 v[206:207], v[144:147], off offset:16
	s_cbranch_vccnz .LBB0_423
	v_pk_mul_f32 v[206:207], v[194:195], v[148:149]
	v_pk_mul_f32 v[208:209], v[196:197], v[150:151]
	v_cvt_pk_bf16_f32 v206, v206, v207
	v_lshl_add_u64 v[204:205], v[204:205], 1, s[34:35]
	v_cvt_pk_bf16_f32 v207, v208, v209
	v_pk_mul_f32 v[210:211], v[198:199], v[146:147]
	v_pk_mul_f32 v[212:213], v[192:193], v[144:145]
	s_nop 0
	v_cvt_pk_bf16_f32 v208, v212, v213
	v_cvt_pk_bf16_f32 v209, v210, v211
	global_store_dwordx4 v[204:205], v[206:209], off
	v_pk_mul_f32 v[204:205], v[134:135], v[150:151]
	v_mov_b32_e32 v212, v148
	v_pk_mul_f32 v[206:207], v[132:133], v[148:149]
	v_pk_mul_f32 v[210:211], v[128:129], v[144:145]
	v_mov_b32_e32 v213, v206
	v_mov_b32_e32 v206, v149
	v_pk_mul_f32 v[148:149], v[206:207], v[206:207]
	v_mov_b32_e32 v207, v204
	v_mov_b32_e32 v204, v151
	v_mov_b32_e32 v206, v150
	v_pk_mul_f32 v[150:151], v[204:205], v[204:205]
	v_pk_fma_f32 v[148:149], v[212:213], v[212:213], v[148:149]
	v_pk_fma_f32 v[150:151], v[206:207], v[206:207], v[150:151]
	v_pk_mul_f32 v[208:209], v[130:131], v[146:147]
	v_pk_add_f32 v[148:149], v[148:149], v[150:151]
	v_mov_b32_e32 v151, v210
	v_mov_b32_e32 v210, v145
	v_mov_b32_e32 v150, v144
	v_pk_mul_f32 v[144:145], v[210:211], v[210:211]
	s_nop 0
	v_pk_fma_f32 v[144:145], v[150:151], v[150:151], v[144:145]
	v_mov_b32_e32 v151, v208
	v_mov_b32_e32 v208, v147
	v_mov_b32_e32 v150, v146
	v_pk_mul_f32 v[146:147], v[208:209], v[208:209]
	s_nop 0
	v_pk_fma_f32 v[146:147], v[150:151], v[150:151], v[146:147]
	s_nop 0
	v_pk_add_f32 v[144:145], v[144:145], v[146:147]
	s_nop 0
	v_pk_add_f32 v[144:145], v[148:149], v[144:145]
	s_nop 0
	v_pk_add_f32 v[184:185], v[184:185], v[144:145]
.LBB0_423:
	v_add_u32_e32 v176, 0x2c000, v176
	s_waitcnt vmcnt(0)
	v_pk_fma_f32 v[142:143], v[6:7], v[200:201], v[142:143]
	v_pk_fma_f32 v[140:141], v[4:5], v[202:203], v[140:141]
	v_pk_fma_f32 v[138:139], v[2:3], v[190:191], v[138:139]
	v_pk_fma_f32 v[136:137], v[0:1], v[188:189], v[136:137]
	v_lshl_add_u64 v[144:145], v[176:177], 2, s[36:37]
	s_and_b64 vcc, exec, s[8:9]
	global_store_dwordx4 v[144:145], v[140:143], off
	global_store_dwordx4 v[144:145], v[136:139], off offset:16
	s_cbranch_vccnz .LBB0_425
	v_pk_mul_f32 v[146:147], v[196:197], v[142:143]
	v_pk_mul_f32 v[144:145], v[194:195], v[140:141]
	v_pk_mul_f32 v[148:149], v[198:199], v[138:139]
	v_pk_mul_f32 v[150:151], v[192:193], v[136:137]
	v_cvt_pk_bf16_f32 v144, v144, v145
	v_cvt_pk_bf16_f32 v145, v146, v147
	v_pk_mul_f32 v[134:135], v[134:135], v[142:143]
	v_cvt_pk_bf16_f32 v146, v150, v151
	v_cvt_pk_bf16_f32 v147, v148, v149
	v_lshl_add_u64 v[148:149], v[176:177], 1, s[34:35]
	v_pk_mul_f32 v[132:133], v[132:133], v[140:141]
	global_store_dwordx4 v[148:149], v[144:147], off
	v_pk_mul_f32 v[128:129], v[128:129], v[136:137]
	v_pk_mul_f32 v[130:131], v[130:131], v[138:139]
	v_mov_b32_e32 v145, v132
	v_mov_b32_e32 v132, v141
	v_mov_b32_e32 v141, v134
	v_mov_b32_e32 v134, v143
	v_mov_b32_e32 v144, v140
	v_pk_mul_f32 v[132:133], v[132:133], v[132:133]
	v_mov_b32_e32 v140, v142
	v_pk_mul_f32 v[134:135], v[134:135], v[134:135]
	v_pk_fma_f32 v[132:133], v[144:145], v[144:145], v[132:133]
	v_pk_fma_f32 v[134:135], v[140:141], v[140:141], v[134:135]
	s_nop 0
	v_pk_add_f32 v[132:133], v[132:133], v[134:135]
	v_mov_b32_e32 v135, v128
	v_mov_b32_e32 v128, v137
	v_mov_b32_e32 v134, v136
	v_pk_mul_f32 v[128:129], v[128:129], v[128:129]
	s_nop 0
	v_pk_fma_f32 v[128:129], v[134:135], v[134:135], v[128:129]
	v_mov_b32_e32 v135, v130
	v_mov_b32_e32 v130, v139
	v_mov_b32_e32 v134, v138
	v_pk_mul_f32 v[130:131], v[130:131], v[130:131]
	s_nop 0
	v_pk_fma_f32 v[130:131], v[134:135], v[134:135], v[130:131]
	s_nop 0
	v_pk_add_f32 v[128:129], v[128:129], v[130:131]
	s_nop 0
	v_pk_add_f32 v[128:129], v[132:133], v[128:129]
	s_nop 0
	v_pk_add_f32 v[186:187], v[186:187], v[128:129]
